# cache-policy experiment: G1 epilogue stores (UA/UC/UZ/UAB) tagged nt so they stream out instead of being flushed at the barrier
# baseline (speedup 1.0000x reference)
.LBB0_180:
	s_cmp_lt_i32 s61, 2
	v_add_u32_e32 v160, s23, v215
	s_cselect_b64 s[36:37], -1, 0
	s_and_b32 s23, s61, -2
	s_cmp_eq_u32 s23, 6
	s_cselect_b64 s[38:39], -1, 0
	s_or_b64 vcc, s[36:37], s[38:39]
	v_ashrrev_i32_e32 v161, 31, v160
	s_waitcnt lgkmcnt(6)
	v_cndmask_b32_e32 v186, 1.0, v212, vcc
	s_waitcnt lgkmcnt(0)
	v_lshl_add_u64 v[188:189], v[160:161], 1, s[0:1]
	v_mad_i64_i32 v[160:161], s[36:37], s30, v184, 0
	s_or_b64 s[0:1], s[34:35], s[38:39]
	v_lshl_add_u64 v[202:203], v[160:161], 1, v[188:189]
	v_pk_mul_f32 v[160:161], v[186:187], v[200:201] op_sel_hi:[0,1]
	v_pk_mul_f32 v[162:163], v[186:187], v[198:199] op_sel_hi:[0,1]
	v_pk_mul_f32 v[164:165], v[186:187], v[196:197] op_sel_hi:[0,1]
	v_pk_mul_f32 v[196:197], v[186:187], v[194:195] op_sel_hi:[0,1]
	v_cvt_pk_bf16_f32 v194, v162, v163
	v_cvt_pk_bf16_f32 v195, v160, v161
	v_cvt_pk_bf16_f32 v196, v196, v197
	v_cvt_pk_bf16_f32 v197, v164, v165
	v_mov_b32_e32 v160, v192
	v_mov_b32_e32 v161, v192
	s_and_b64 s[0:1], s[18:19], s[0:1]
	v_mov_b32_e32 v193, v192
	global_store_dwordx4 v[202:203], v[194:197], off nt
	v_pk_fma_f32 v[150:151], v[150:151], v[160:161], v[110:111]
	v_pk_fma_f32 v[148:149], v[148:149], v[192:193], v[108:109]
	v_pk_fma_f32 v[194:195], v[146:147], v[160:161], v[106:107]
	v_cndmask_b32_e64 v146, 0, 1, s[0:1]
	v_cmp_ne_u32_e64 s[46:47], 1, v146
	s_andn2_b64 vcc, exec, s[0:1]
	v_pk_fma_f32 v[144:145], v[144:145], v[192:193], v[104:105]
	s_cbranch_vccnz .LBB0_184
	v_mbcnt_hi_u32_b32 v146, -1, v207
	v_and_b32_e32 v160, 64, v146
	v_xor_b32_e32 v147, 16, v146
	v_add_u32_e32 v160, 64, v160
	v_cmp_lt_i32_e32 vcc, v147, v160
	s_nop 1
	v_cndmask_b32_e32 v146, v146, v147, vcc
	v_lshlrev_b32_e32 v160, 2, v146
	ds_bpermute_b32 v196, v160, v148
	ds_bpermute_b32 v146, v160, v144
	ds_bpermute_b32 v197, v160, v149
	ds_bpermute_b32 v147, v160, v145
	ds_bpermute_b32 v198, v160, v150
	ds_bpermute_b32 v192, v160, v194
	ds_bpermute_b32 v199, v160, v151
	ds_bpermute_b32 v193, v160, v195
	s_and_saveexec_b64 s[0:1], s[40:41]
	s_cbranch_execz .LBB0_183
	v_lshl_add_u64 v[160:161], s[14:15], 0, v[190:191]
	global_load_dwordx4 v[218:221], v[160:161], off offset:32
	global_load_dwordx4 v[222:225], v[160:161], off offset:48
	global_load_dwordx4 v[226:229], v[160:161], off
	global_load_dwordx4 v[230:233], v[160:161], off offset:16
	s_waitcnt vmcnt(3) lgkmcnt(1)
	v_pk_mul_f32 v[160:161], v[220:221], v[198:199]
	v_pk_mul_f32 v[162:163], v[218:219], v[196:197]
	s_waitcnt vmcnt(2) lgkmcnt(0)
	v_pk_mul_f32 v[164:165], v[224:225], v[192:193]
	v_pk_mul_f32 v[146:147], v[222:223], v[146:147]
	v_pk_mul_f32 v[162:163], v[174:175], v[162:163]
	v_pk_mul_f32 v[160:161], v[176:177], v[160:161]
	v_pk_mul_f32 v[146:147], v[174:175], v[146:147]
	v_pk_mul_f32 v[164:165], v[176:177], v[164:165]
	s_waitcnt vmcnt(1)
	v_pk_fma_f32 v[150:151], v[150:151], v[228:229], v[160:161]
	v_pk_fma_f32 v[148:149], v[148:149], v[226:227], v[162:163]
	s_waitcnt vmcnt(0)
	v_pk_fma_f32 v[194:195], v[194:195], v[232:233], v[164:165]
	v_pk_fma_f32 v[144:145], v[144:145], v[230:231], v[146:147]

.LBB0_184:
	v_mov_b32_e32 v187, v186
	s_waitcnt lgkmcnt(6)
	v_mov_b32_e32 v146, v186
	s_waitcnt lgkmcnt(4)
	v_mov_b32_e32 v147, v186
	v_pk_mul_f32 v[150:151], v[146:147], v[150:151]
	v_pk_mul_f32 v[148:149], v[186:187], v[148:149]
	v_pk_mul_f32 v[160:161], v[146:147], v[194:195]
	v_pk_mul_f32 v[144:145], v[186:187], v[144:145]
	v_cvt_pk_bf16_f32 v148, v148, v149
	v_cvt_pk_bf16_f32 v149, v150, v151
	v_cvt_pk_bf16_f32 v150, v144, v145
	v_cvt_pk_bf16_f32 v151, v160, v161
	global_store_dwordx4 v[202:203], v[148:151], off offset:256 nt
	s_and_b64 vcc, exec, s[44:45]
	s_nop 0
	v_add_u32_e32 v148, 16, v184
	v_ashrrev_i32_e32 v149, 31, v148
	v_lshlrev_b64 v[144:145], 6, v[148:149]
	v_lshl_add_u64 v[150:151], s[12:13], 0, v[144:145]
	s_waitcnt lgkmcnt(0)
	global_load_dwordx4 v[190:193], v[150:151], off
	global_load_dwordx4 v[194:197], v[150:151], off offset:32
	global_load_dwordx4 v[198:201], v[150:151], off offset:16
	global_load_dwordx4 v[202:205], v[150:151], off offset:48
	s_waitcnt vmcnt(3)
	v_mov_b32_e32 v150, v190
	s_waitcnt vmcnt(2)
	v_mov_b32_e32 v151, v194
	v_mov_b32_e32 v194, v191
	v_mov_b32_e32 v160, v192
	v_mov_b32_e32 v161, v196
	v_mov_b32_e32 v196, v193
	s_waitcnt vmcnt(1)
	v_mov_b32_e32 v162, v198
	s_waitcnt vmcnt(0)
	v_mov_b32_e32 v163, v202
	v_mov_b32_e32 v202, v199
	v_mov_b32_e32 v164, v200
	v_mov_b32_e32 v165, v204
	v_mov_b32_e32 v204, v201
	v_pk_add_f32 v[150:151], v[150:151], v[194:195]
	v_pk_add_f32 v[160:161], v[160:161], v[196:197]
	v_pk_add_f32 v[162:163], v[162:163], v[202:203]
	v_pk_add_f32 v[164:165], v[164:165], v[204:205]
	v_pk_add_f32 v[150:151], v[150:151], v[160:161]
	v_pk_add_f32 v[160:161], v[162:163], v[164:165]
	s_nop 0
	v_pk_add_f32 v[150:151], v[150:151], v[160:161]
	s_nop 0
	v_add_f32_e32 v149, v150, v151
	v_fmamk_f32 v149, v149, 0x3a800000, v208
	v_mul_f32_e32 v150, 0x4b800000, v149
	v_cmp_gt_f32_e64 s[0:1], s94, v149
	s_nop 1
	v_cndmask_b32_e64 v149, v149, v150, s[0:1]
	v_rsq_f32_e32 v149, v149
	s_nop 0
	v_mul_f32_e32 v150, 0x45800000, v149
	v_cndmask_b32_e64 v150, v149, v150, s[0:1]
	v_pk_fma_f32 v[196:197], v[70:71], v[150:151], v[30:31] op_sel_hi:[1,0,1]
	v_pk_fma_f32 v[194:195], v[68:69], v[150:151], v[28:29] op_sel_hi:[1,0,1]
	v_pk_fma_f32 v[192:193], v[66:67], v[150:151], v[26:27] op_sel_hi:[1,0,1]
	v_pk_fma_f32 v[190:191], v[64:65], v[150:151], v[24:25] op_sel_hi:[1,0,1]
	s_cbranch_vccnz .LBB0_189
	s_add_i32 s0, s61, -6
	s_cmp_gt_u32 s0, 2
	s_cselect_b64 s[0:1], -1, 0
	s_xor_b64 s[36:37], s[34:35], -1
	s_and_b64 s[0:1], s[36:37], s[0:1]
	s_and_b64 vcc, exec, s[0:1]
	s_cbranch_vccnz .LBB0_189
	v_mbcnt_hi_u32_b32 v149, -1, v207
	v_and_b32_e32 v160, 64, v149
	v_xor_b32_e32 v151, 16, v149
	v_add_u32_e32 v160, 64, v160
	v_cmp_lt_i32_e32 vcc, v151, v160
	s_nop 1
	v_cndmask_b32_e32 v149, v149, v151, vcc
	v_lshlrev_b32_e32 v149, 2, v149
	ds_bpermute_b32 v202, v149, v194
	ds_bpermute_b32 v198, v149, v190
	ds_bpermute_b32 v203, v149, v195
	ds_bpermute_b32 v199, v149, v191
	ds_bpermute_b32 v204, v149, v196
	ds_bpermute_b32 v200, v149, v192
	ds_bpermute_b32 v205, v149, v197
	ds_bpermute_b32 v201, v149, v193
	s_and_saveexec_b64 s[0:1], s[40:41]
	s_cbranch_execz .LBB0_188
	v_lshl_add_u64 v[160:161], s[14:15], 0, v[144:145]
	global_load_dwordx4 v[218:221], v[160:161], off offset:32
	global_load_dwordx4 v[222:225], v[160:161], off offset:48
	global_load_dwordx4 v[226:229], v[160:161], off
	global_load_dwordx4 v[230:233], v[160:161], off offset:16
	s_waitcnt vmcnt(3) lgkmcnt(1)
	v_pk_mul_f32 v[160:161], v[220:221], v[204:205]
	v_pk_mul_f32 v[162:163], v[218:219], v[202:203]
	s_waitcnt vmcnt(2) lgkmcnt(0)
	v_pk_mul_f32 v[164:165], v[224:225], v[200:201]
	v_pk_mul_f32 v[198:199], v[222:223], v[198:199]
	v_pk_mul_f32 v[162:163], v[174:175], v[162:163]
	v_pk_mul_f32 v[160:161], v[176:177], v[160:161]
	v_pk_mul_f32 v[198:199], v[174:175], v[198:199]
	v_pk_mul_f32 v[164:165], v[176:177], v[164:165]
	s_waitcnt vmcnt(1)
	v_pk_fma_f32 v[196:197], v[196:197], v[228:229], v[160:161]
	v_pk_fma_f32 v[194:195], v[194:195], v[226:227], v[162:163]
	s_waitcnt vmcnt(0)
	v_pk_fma_f32 v[192:193], v[192:193], v[232:233], v[164:165]
	v_pk_fma_f32 v[190:191], v[190:191], v[230:231], v[198:199]

.LBB0_189:
	v_pk_mul_f32 v[160:161], v[146:147], v[196:197]
	v_pk_mul_f32 v[146:147], v[146:147], v[192:193]
	v_mov_b32_e32 v151, v150
	v_mad_i64_i32 v[148:149], s[0:1], s30, v148, 0
	v_pk_mul_f32 v[162:163], v[186:187], v[194:195]
	v_pk_mul_f32 v[164:165], v[186:187], v[190:191]
	v_cvt_pk_bf16_f32 v193, v146, v147
	v_mov_b32_e32 v146, v150
	v_mov_b32_e32 v147, v150
	v_lshl_add_u64 v[148:149], v[148:149], 1, v[188:189]
	v_cvt_pk_bf16_f32 v190, v162, v163
	v_cvt_pk_bf16_f32 v191, v160, v161
	v_cvt_pk_bf16_f32 v192, v164, v165
	v_pk_fma_f32 v[142:143], v[142:143], v[146:147], v[110:111]
	v_pk_fma_f32 v[140:141], v[140:141], v[150:151], v[108:109]
	v_pk_fma_f32 v[146:147], v[138:139], v[146:147], v[106:107]
	s_and_b64 vcc, exec, s[46:47]
	v_pk_fma_f32 v[136:137], v[136:137], v[150:151], v[104:105]
	global_store_dwordx4 v[148:149], v[190:193], off nt
	s_cbranch_vccnz .LBB0_193
	v_mbcnt_hi_u32_b32 v138, -1, v207
	v_and_b32_e32 v150, 64, v138
	v_xor_b32_e32 v139, 16, v138
	v_add_u32_e32 v150, 64, v150
	v_cmp_lt_i32_e32 vcc, v139, v150
	s_nop 1
	v_cndmask_b32_e32 v138, v138, v139, vcc
	v_lshlrev_b32_e32 v151, 2, v138
	ds_bpermute_b32 v190, v151, v140
	ds_bpermute_b32 v138, v151, v136
	ds_bpermute_b32 v191, v151, v141
	ds_bpermute_b32 v139, v151, v137
	ds_bpermute_b32 v192, v151, v142
	ds_bpermute_b32 v150, v151, v146
	ds_bpermute_b32 v193, v151, v143
	ds_bpermute_b32 v151, v151, v147
	s_and_saveexec_b64 s[0:1], s[40:41]
	s_cbranch_execz .LBB0_192
	v_lshl_add_u64 v[144:145], s[14:15], 0, v[144:145]
	global_load_dwordx4 v[194:197], v[144:145], off offset:32
	s_waitcnt lgkmcnt(8)
	global_load_dwordx4 v[198:201], v[144:145], off offset:48
	global_load_dwordx4 v[202:205], v[144:145], off
	global_load_dwordx4 v[218:221], v[144:145], off offset:16
	s_waitcnt vmcnt(3) lgkmcnt(1)
	v_pk_mul_f32 v[144:145], v[196:197], v[192:193]
	v_pk_mul_f32 v[160:161], v[194:195], v[190:191]
	s_waitcnt vmcnt(2) lgkmcnt(0)
	v_pk_mul_f32 v[150:151], v[200:201], v[150:151]
	v_pk_mul_f32 v[138:139], v[198:199], v[138:139]
	v_pk_mul_f32 v[160:161], v[174:175], v[160:161]
	v_pk_mul_f32 v[144:145], v[176:177], v[144:145]
	v_pk_mul_f32 v[138:139], v[174:175], v[138:139]
	v_pk_mul_f32 v[150:151], v[176:177], v[150:151]
	s_waitcnt vmcnt(1)
	v_pk_fma_f32 v[142:143], v[142:143], v[204:205], v[144:145]
	v_pk_fma_f32 v[140:141], v[140:141], v[202:203], v[160:161]
	s_waitcnt vmcnt(0)
	v_pk_fma_f32 v[146:147], v[146:147], v[220:221], v[150:151]
	v_pk_fma_f32 v[136:137], v[136:137], v[218:219], v[138:139]

.LBB0_193:
	s_waitcnt lgkmcnt(6)
	v_mov_b32_e32 v138, v186
	s_waitcnt lgkmcnt(4)
	v_mov_b32_e32 v139, v186
	v_pk_mul_f32 v[142:143], v[138:139], v[142:143]
	v_pk_mul_f32 v[140:141], v[186:187], v[140:141]
	v_pk_mul_f32 v[144:145], v[138:139], v[146:147]
	v_pk_mul_f32 v[136:137], v[186:187], v[136:137]
	v_cvt_pk_bf16_f32 v140, v140, v141
	v_cvt_pk_bf16_f32 v141, v142, v143
	v_cvt_pk_bf16_f32 v142, v136, v137
	v_cvt_pk_bf16_f32 v143, v144, v145
	global_store_dwordx4 v[148:149], v[140:143], off offset:256 nt
	s_and_b64 vcc, exec, s[44:45]
	s_nop 0
	v_add_u32_e32 v140, 32, v184
	v_ashrrev_i32_e32 v141, 31, v140
	v_lshlrev_b64 v[136:137], 6, v[140:141]
	s_waitcnt lgkmcnt(0)
	v_lshl_add_u64 v[150:151], s[12:13], 0, v[136:137]
	global_load_dwordx4 v[142:145], v[150:151], off
	global_load_dwordx4 v[146:149], v[150:151], off offset:32
	global_load_dwordx4 v[190:193], v[150:151], off offset:16
	global_load_dwordx4 v[194:197], v[150:151], off offset:48
	s_waitcnt vmcnt(3)
	v_mov_b32_e32 v150, v142
	s_waitcnt vmcnt(2)
	v_mov_b32_e32 v151, v146
	v_mov_b32_e32 v146, v143
	v_mov_b32_e32 v142, v144
	v_mov_b32_e32 v143, v148
	v_mov_b32_e32 v148, v145
	s_waitcnt vmcnt(1)
	v_mov_b32_e32 v144, v190
	s_waitcnt vmcnt(0)
	v_mov_b32_e32 v145, v194
	v_mov_b32_e32 v194, v191
	v_mov_b32_e32 v160, v192
	v_mov_b32_e32 v161, v196
	v_mov_b32_e32 v196, v193
	v_pk_add_f32 v[146:147], v[150:151], v[146:147]
	v_pk_add_f32 v[142:143], v[142:143], v[148:149]
	v_pk_add_f32 v[144:145], v[144:145], v[194:195]
	v_pk_add_f32 v[148:149], v[160:161], v[196:197]
	v_pk_add_f32 v[142:143], v[146:147], v[142:143]
	v_pk_add_f32 v[144:145], v[144:145], v[148:149]
	s_nop 0
	v_pk_add_f32 v[142:143], v[142:143], v[144:145]
	s_nop 0
	v_add_f32_e32 v141, v142, v143
	v_fmamk_f32 v141, v141, 0x3a800000, v208
	v_mul_f32_e32 v142, 0x4b800000, v141
	v_cmp_gt_f32_e64 s[0:1], s94, v141
	s_nop 1
	v_cndmask_b32_e64 v141, v141, v142, s[0:1]
	v_rsq_f32_e32 v141, v141
	s_nop 0
	v_mul_f32_e32 v142, 0x45800000, v141
	v_cndmask_b32_e64 v142, v141, v142, s[0:1]
	v_pk_fma_f32 v[150:151], v[62:63], v[142:143], v[30:31] op_sel_hi:[1,0,1]
	v_pk_fma_f32 v[148:149], v[60:61], v[142:143], v[28:29] op_sel_hi:[1,0,1]
	v_pk_fma_f32 v[146:147], v[58:59], v[142:143], v[26:27] op_sel_hi:[1,0,1]
	v_pk_fma_f32 v[144:145], v[56:57], v[142:143], v[24:25] op_sel_hi:[1,0,1]
	s_cbranch_vccnz .LBB0_198
	s_add_i32 s0, s61, -6
	s_cmp_gt_u32 s0, 2
	s_cselect_b64 s[0:1], -1, 0
	s_xor_b64 s[36:37], s[34:35], -1
	s_and_b64 s[0:1], s[36:37], s[0:1]
	s_and_b64 vcc, exec, s[0:1]
	s_cbranch_vccnz .LBB0_198
	v_mbcnt_hi_u32_b32 v141, -1, v207
	v_and_b32_e32 v160, 64, v141
	v_xor_b32_e32 v143, 16, v141
	v_add_u32_e32 v160, 64, v160
	v_cmp_lt_i32_e32 vcc, v143, v160
	s_nop 1
	v_cndmask_b32_e32 v141, v141, v143, vcc
	v_lshlrev_b32_e32 v141, 2, v141
	ds_bpermute_b32 v194, v141, v148
	ds_bpermute_b32 v190, v141, v144
	ds_bpermute_b32 v195, v141, v149
	ds_bpermute_b32 v191, v141, v145
	ds_bpermute_b32 v196, v141, v150
	ds_bpermute_b32 v192, v141, v146
	ds_bpermute_b32 v197, v141, v151
	ds_bpermute_b32 v193, v141, v147
	s_and_saveexec_b64 s[0:1], s[40:41]
	s_cbranch_execz .LBB0_197
	v_lshl_add_u64 v[160:161], s[14:15], 0, v[136:137]
	global_load_dwordx4 v[198:201], v[160:161], off offset:32
	global_load_dwordx4 v[202:205], v[160:161], off offset:48
	global_load_dwordx4 v[218:221], v[160:161], off
	global_load_dwordx4 v[222:225], v[160:161], off offset:16
	s_waitcnt vmcnt(3) lgkmcnt(1)
	v_pk_mul_f32 v[160:161], v[200:201], v[196:197]
	v_pk_mul_f32 v[162:163], v[198:199], v[194:195]
	s_waitcnt vmcnt(2) lgkmcnt(0)
	v_pk_mul_f32 v[164:165], v[204:205], v[192:193]
	v_pk_mul_f32 v[190:191], v[202:203], v[190:191]
	v_pk_mul_f32 v[162:163], v[174:175], v[162:163]
	v_pk_mul_f32 v[160:161], v[176:177], v[160:161]
	v_pk_mul_f32 v[190:191], v[174:175], v[190:191]
	v_pk_mul_f32 v[164:165], v[176:177], v[164:165]
	s_waitcnt vmcnt(1)
	v_pk_fma_f32 v[150:151], v[150:151], v[220:221], v[160:161]
	v_pk_fma_f32 v[148:149], v[148:149], v[218:219], v[162:163]
	s_waitcnt vmcnt(0)
	v_pk_fma_f32 v[146:147], v[146:147], v[224:225], v[164:165]
	v_pk_fma_f32 v[144:145], v[144:145], v[222:223], v[190:191]

.LBB0_198:
	v_pk_mul_f32 v[150:151], v[138:139], v[150:151]
	v_pk_mul_f32 v[138:139], v[138:139], v[146:147]
	v_pk_mul_f32 v[146:147], v[186:187], v[144:145]
	v_mov_b32_e32 v143, v142
	v_mad_i64_i32 v[140:141], s[0:1], s30, v140, 0
	v_pk_mul_f32 v[148:149], v[186:187], v[148:149]
	v_cvt_pk_bf16_f32 v146, v146, v147
	v_cvt_pk_bf16_f32 v147, v138, v139
	v_mov_b32_e32 v138, v142
	v_mov_b32_e32 v139, v142
	v_lshl_add_u64 v[140:141], v[140:141], 1, v[188:189]
	v_cvt_pk_bf16_f32 v144, v148, v149
	v_cvt_pk_bf16_f32 v145, v150, v151
	v_pk_fma_f32 v[134:135], v[134:135], v[138:139], v[110:111]
	v_pk_fma_f32 v[132:133], v[132:133], v[142:143], v[108:109]
	v_pk_fma_f32 v[138:139], v[130:131], v[138:139], v[106:107]
	s_and_b64 vcc, exec, s[46:47]
	v_pk_fma_f32 v[128:129], v[128:129], v[142:143], v[104:105]
	global_store_dwordx4 v[140:141], v[144:147], off nt
	s_cbranch_vccnz .LBB0_202
	v_mbcnt_hi_u32_b32 v130, -1, v207
	v_and_b32_e32 v142, 64, v130
	v_xor_b32_e32 v131, 16, v130
	v_add_u32_e32 v142, 64, v142
	v_cmp_lt_i32_e32 vcc, v131, v142
	s_nop 1
	v_cndmask_b32_e32 v130, v130, v131, vcc
	v_lshlrev_b32_e32 v143, 2, v130
	ds_bpermute_b32 v144, v143, v132
	ds_bpermute_b32 v130, v143, v128
	ds_bpermute_b32 v145, v143, v133
	ds_bpermute_b32 v131, v143, v129
	ds_bpermute_b32 v146, v143, v134
	ds_bpermute_b32 v142, v143, v138
	ds_bpermute_b32 v147, v143, v135
	ds_bpermute_b32 v143, v143, v139
	s_and_saveexec_b64 s[0:1], s[40:41]
	s_cbranch_execz .LBB0_201
	v_lshl_add_u64 v[136:137], s[14:15], 0, v[136:137]
	global_load_dwordx4 v[148:151], v[136:137], off offset:32
	s_waitcnt lgkmcnt(8)
	global_load_dwordx4 v[190:193], v[136:137], off offset:48
	global_load_dwordx4 v[194:197], v[136:137], off
	global_load_dwordx4 v[198:201], v[136:137], off offset:16
	s_waitcnt vmcnt(3) lgkmcnt(1)
	v_pk_mul_f32 v[136:137], v[150:151], v[146:147]
	v_pk_mul_f32 v[144:145], v[148:149], v[144:145]
	s_waitcnt vmcnt(2) lgkmcnt(0)
	v_pk_mul_f32 v[142:143], v[192:193], v[142:143]
	v_pk_mul_f32 v[130:131], v[190:191], v[130:131]
	v_pk_mul_f32 v[144:145], v[174:175], v[144:145]
	v_pk_mul_f32 v[136:137], v[176:177], v[136:137]
	v_pk_mul_f32 v[130:131], v[174:175], v[130:131]
	v_pk_mul_f32 v[142:143], v[176:177], v[142:143]
	s_waitcnt vmcnt(1)
	v_pk_fma_f32 v[134:135], v[134:135], v[196:197], v[136:137]
	v_pk_fma_f32 v[132:133], v[132:133], v[194:195], v[144:145]
	s_waitcnt vmcnt(0)
	v_pk_fma_f32 v[138:139], v[138:139], v[200:201], v[142:143]
	v_pk_fma_f32 v[128:129], v[128:129], v[198:199], v[130:131]

.LBB0_202:
	s_waitcnt lgkmcnt(6)
	v_mov_b32_e32 v130, v186
	s_waitcnt lgkmcnt(4)
	v_mov_b32_e32 v131, v186
	v_pk_mul_f32 v[134:135], v[130:131], v[134:135]
	v_pk_mul_f32 v[132:133], v[186:187], v[132:133]
	v_pk_mul_f32 v[136:137], v[130:131], v[138:139]
	v_pk_mul_f32 v[128:129], v[186:187], v[128:129]
	v_cvt_pk_bf16_f32 v132, v132, v133
	v_cvt_pk_bf16_f32 v133, v134, v135
	v_cvt_pk_bf16_f32 v134, v128, v129
	v_cvt_pk_bf16_f32 v135, v136, v137
	global_store_dwordx4 v[140:141], v[132:135], off offset:256 nt
	s_and_b64 vcc, exec, s[44:45]
	s_nop 0
	v_add_u32_e32 v132, 48, v184
	v_ashrrev_i32_e32 v133, 31, v132
	v_lshlrev_b64 v[128:129], 6, v[132:133]
	s_waitcnt lgkmcnt(1)
	v_lshl_add_u64 v[146:147], s[12:13], 0, v[128:129]
	global_load_dwordx4 v[134:137], v[146:147], off
	global_load_dwordx4 v[138:141], v[146:147], off offset:32
	s_waitcnt lgkmcnt(0)
	global_load_dwordx4 v[142:145], v[146:147], off offset:16
	s_nop 0
	global_load_dwordx4 v[146:149], v[146:147], off offset:48
	s_waitcnt vmcnt(3)
	v_mov_b32_e32 v150, v134
	s_waitcnt vmcnt(2)
	v_mov_b32_e32 v151, v138
	v_mov_b32_e32 v138, v135
	v_mov_b32_e32 v134, v136
	v_mov_b32_e32 v135, v140
	v_mov_b32_e32 v140, v137
	s_waitcnt vmcnt(1)
	v_mov_b32_e32 v136, v142
	s_waitcnt vmcnt(0)
	v_mov_b32_e32 v137, v146
	v_mov_b32_e32 v146, v143
	v_mov_b32_e32 v142, v144
	v_mov_b32_e32 v143, v148
	v_mov_b32_e32 v148, v145
	v_pk_add_f32 v[138:139], v[150:151], v[138:139]
	v_pk_add_f32 v[134:135], v[134:135], v[140:141]
	v_pk_add_f32 v[136:137], v[136:137], v[146:147]
	v_pk_add_f32 v[140:141], v[142:143], v[148:149]
	v_pk_add_f32 v[134:135], v[138:139], v[134:135]
	v_pk_add_f32 v[136:137], v[136:137], v[140:141]
	s_nop 0
	v_pk_add_f32 v[134:135], v[134:135], v[136:137]
	s_nop 0
	v_add_f32_e32 v133, v134, v135
	v_fmamk_f32 v133, v133, 0x3a800000, v208
	v_mul_f32_e32 v134, 0x4b800000, v133
	v_cmp_gt_f32_e64 s[0:1], s94, v133
	s_nop 1
	v_cndmask_b32_e64 v133, v133, v134, s[0:1]
	v_rsq_f32_e32 v133, v133
	s_nop 0
	v_mul_f32_e32 v134, 0x45800000, v133
	v_cndmask_b32_e64 v134, v133, v134, s[0:1]
	v_pk_fma_f32 v[142:143], v[54:55], v[134:135], v[30:31] op_sel_hi:[1,0,1]
	v_pk_fma_f32 v[140:141], v[52:53], v[134:135], v[28:29] op_sel_hi:[1,0,1]
	v_pk_fma_f32 v[138:139], v[50:51], v[134:135], v[26:27] op_sel_hi:[1,0,1]
	v_pk_fma_f32 v[136:137], v[48:49], v[134:135], v[24:25] op_sel_hi:[1,0,1]
	s_cbranch_vccnz .LBB0_207
	s_add_i32 s0, s61, -6
	s_cmp_gt_u32 s0, 2
	s_cselect_b64 s[0:1], -1, 0
	s_xor_b64 s[36:37], s[34:35], -1
	s_and_b64 s[0:1], s[36:37], s[0:1]
	s_and_b64 vcc, exec, s[0:1]
	s_cbranch_vccnz .LBB0_207
	v_mbcnt_hi_u32_b32 v133, -1, v207
	v_and_b32_e32 v144, 64, v133
	v_xor_b32_e32 v135, 16, v133
	v_add_u32_e32 v144, 64, v144
	v_cmp_lt_i32_e32 vcc, v135, v144
	s_nop 1
	v_cndmask_b32_e32 v133, v133, v135, vcc
	v_lshlrev_b32_e32 v133, 2, v133
	ds_bpermute_b32 v148, v133, v140
	ds_bpermute_b32 v144, v133, v136
	ds_bpermute_b32 v149, v133, v141
	ds_bpermute_b32 v145, v133, v137
	ds_bpermute_b32 v150, v133, v142
	ds_bpermute_b32 v146, v133, v138
	ds_bpermute_b32 v151, v133, v143
	ds_bpermute_b32 v147, v133, v139
	s_and_saveexec_b64 s[0:1], s[40:41]
	s_cbranch_execz .LBB0_206
	v_lshl_add_u64 v[160:161], s[14:15], 0, v[128:129]
	global_load_dwordx4 v[190:193], v[160:161], off offset:32
	global_load_dwordx4 v[194:197], v[160:161], off offset:48
	global_load_dwordx4 v[198:201], v[160:161], off
	global_load_dwordx4 v[202:205], v[160:161], off offset:16
	s_waitcnt vmcnt(3) lgkmcnt(1)
	v_pk_mul_f32 v[150:151], v[192:193], v[150:151]
	v_pk_mul_f32 v[148:149], v[190:191], v[148:149]
	s_waitcnt vmcnt(2) lgkmcnt(0)
	v_pk_mul_f32 v[146:147], v[196:197], v[146:147]
	v_pk_mul_f32 v[144:145], v[194:195], v[144:145]
	v_pk_mul_f32 v[148:149], v[174:175], v[148:149]
	v_pk_mul_f32 v[150:151], v[176:177], v[150:151]
	v_pk_mul_f32 v[144:145], v[174:175], v[144:145]
	v_pk_mul_f32 v[146:147], v[176:177], v[146:147]
	s_waitcnt vmcnt(1)
	v_pk_fma_f32 v[142:143], v[142:143], v[200:201], v[150:151]
	v_pk_fma_f32 v[140:141], v[140:141], v[198:199], v[148:149]
	s_waitcnt vmcnt(0)
	v_pk_fma_f32 v[138:139], v[138:139], v[204:205], v[146:147]
	v_pk_fma_f32 v[136:137], v[136:137], v[202:203], v[144:145]

.LBB0_207:
	v_pk_mul_f32 v[142:143], v[130:131], v[142:143]
	v_pk_mul_f32 v[130:131], v[130:131], v[138:139]
	v_pk_mul_f32 v[138:139], v[186:187], v[136:137]
	v_mov_b32_e32 v135, v134
	v_mad_i64_i32 v[132:133], s[0:1], s30, v132, 0
	v_pk_mul_f32 v[140:141], v[186:187], v[140:141]
	v_cvt_pk_bf16_f32 v138, v138, v139
	v_cvt_pk_bf16_f32 v139, v130, v131
	v_mov_b32_e32 v130, v134
	v_mov_b32_e32 v131, v134
	v_lshl_add_u64 v[132:133], v[132:133], 1, v[188:189]
	v_cvt_pk_bf16_f32 v136, v140, v141
	v_cvt_pk_bf16_f32 v137, v142, v143
	v_pk_fma_f32 v[126:127], v[126:127], v[130:131], v[110:111]
	v_pk_fma_f32 v[124:125], v[124:125], v[134:135], v[108:109]
	v_pk_fma_f32 v[130:131], v[122:123], v[130:131], v[106:107]
	s_and_b64 vcc, exec, s[46:47]
	v_pk_fma_f32 v[120:121], v[120:121], v[134:135], v[104:105]
	global_store_dwordx4 v[132:133], v[136:139], off nt
	s_cbranch_vccnz .LBB0_211
	v_mbcnt_hi_u32_b32 v122, -1, v207
	v_and_b32_e32 v134, 64, v122
	v_xor_b32_e32 v123, 16, v122
	v_add_u32_e32 v134, 64, v134
	v_cmp_lt_i32_e32 vcc, v123, v134
	s_nop 1
	v_cndmask_b32_e32 v122, v122, v123, vcc
	v_lshlrev_b32_e32 v135, 2, v122
	ds_bpermute_b32 v136, v135, v124
	ds_bpermute_b32 v122, v135, v120
	ds_bpermute_b32 v137, v135, v125
	ds_bpermute_b32 v123, v135, v121
	ds_bpermute_b32 v138, v135, v126
	ds_bpermute_b32 v134, v135, v130
	ds_bpermute_b32 v139, v135, v127
	ds_bpermute_b32 v135, v135, v131
	s_and_saveexec_b64 s[0:1], s[40:41]
	s_cbranch_execz .LBB0_210
	v_lshl_add_u64 v[128:129], s[14:15], 0, v[128:129]
	global_load_dwordx4 v[140:143], v[128:129], off offset:32
	s_waitcnt lgkmcnt(8)
	global_load_dwordx4 v[144:147], v[128:129], off offset:48
	global_load_dwordx4 v[148:151], v[128:129], off
	global_load_dwordx4 v[190:193], v[128:129], off offset:16
	s_waitcnt vmcnt(3) lgkmcnt(1)
	v_pk_mul_f32 v[128:129], v[142:143], v[138:139]
	v_pk_mul_f32 v[136:137], v[140:141], v[136:137]
	s_waitcnt vmcnt(2) lgkmcnt(0)
	v_pk_mul_f32 v[134:135], v[146:147], v[134:135]
	v_pk_mul_f32 v[122:123], v[144:145], v[122:123]
	v_pk_mul_f32 v[136:137], v[174:175], v[136:137]
	v_pk_mul_f32 v[128:129], v[176:177], v[128:129]
	v_pk_mul_f32 v[122:123], v[174:175], v[122:123]
	v_pk_mul_f32 v[134:135], v[176:177], v[134:135]
	s_waitcnt vmcnt(1)
	v_pk_fma_f32 v[126:127], v[126:127], v[150:151], v[128:129]
	v_pk_fma_f32 v[124:125], v[124:125], v[148:149], v[136:137]
	s_waitcnt vmcnt(0)
	v_pk_fma_f32 v[130:131], v[130:131], v[192:193], v[134:135]
	v_pk_fma_f32 v[120:121], v[120:121], v[190:191], v[122:123]

.LBB0_211:
	s_waitcnt lgkmcnt(6)
	v_mov_b32_e32 v122, v186
	s_waitcnt lgkmcnt(4)
	v_mov_b32_e32 v123, v186
	v_pk_mul_f32 v[126:127], v[122:123], v[126:127]
	v_pk_mul_f32 v[124:125], v[186:187], v[124:125]
	v_pk_mul_f32 v[128:129], v[122:123], v[130:131]
	v_pk_mul_f32 v[120:121], v[186:187], v[120:121]
	v_cvt_pk_bf16_f32 v124, v124, v125
	v_cvt_pk_bf16_f32 v125, v126, v127
	v_cvt_pk_bf16_f32 v126, v120, v121
	v_cvt_pk_bf16_f32 v127, v128, v129
	global_store_dwordx4 v[132:133], v[124:127], off offset:256 nt
	s_and_b64 vcc, exec, s[44:45]
	s_nop 0
	v_add_u32_e32 v124, 0x80, v184
	v_ashrrev_i32_e32 v125, 31, v124
	v_lshlrev_b64 v[120:121], 6, v[124:125]
	s_waitcnt lgkmcnt(1)
	v_lshl_add_u64 v[138:139], s[12:13], 0, v[120:121]
	global_load_dwordx4 v[126:129], v[138:139], off
	global_load_dwordx4 v[130:133], v[138:139], off offset:32
	s_waitcnt lgkmcnt(0)
	global_load_dwordx4 v[134:137], v[138:139], off offset:16
	s_nop 0
	global_load_dwordx4 v[138:141], v[138:139], off offset:48
	s_waitcnt vmcnt(3)
	v_mov_b32_e32 v142, v126
	s_waitcnt vmcnt(2)
	v_mov_b32_e32 v143, v130
	v_mov_b32_e32 v130, v127
	v_mov_b32_e32 v126, v128
	v_mov_b32_e32 v127, v132
	v_mov_b32_e32 v132, v129
	s_waitcnt vmcnt(1)
	v_mov_b32_e32 v128, v134
	s_waitcnt vmcnt(0)
	v_mov_b32_e32 v129, v138
	v_mov_b32_e32 v138, v135
	v_mov_b32_e32 v134, v136
	v_mov_b32_e32 v135, v140
	v_mov_b32_e32 v140, v137
	v_pk_add_f32 v[130:131], v[142:143], v[130:131]
	v_pk_add_f32 v[126:127], v[126:127], v[132:133]
	v_pk_add_f32 v[128:129], v[128:129], v[138:139]
	v_pk_add_f32 v[132:133], v[134:135], v[140:141]
	v_pk_add_f32 v[126:127], v[130:131], v[126:127]
	v_pk_add_f32 v[128:129], v[128:129], v[132:133]
	s_nop 0
	v_pk_add_f32 v[126:127], v[126:127], v[128:129]
	s_nop 0
	v_add_f32_e32 v125, v126, v127
	v_fmamk_f32 v125, v125, 0x3a800000, v208
	v_mul_f32_e32 v126, 0x4b800000, v125
	v_cmp_gt_f32_e64 s[0:1], s94, v125
	s_nop 1
	v_cndmask_b32_e64 v125, v125, v126, s[0:1]
	v_rsq_f32_e32 v125, v125
	s_nop 0
	v_mul_f32_e32 v126, 0x45800000, v125
	v_cndmask_b32_e64 v126, v125, v126, s[0:1]
	v_pk_fma_f32 v[134:135], v[46:47], v[126:127], v[30:31] op_sel_hi:[1,0,1]
	v_pk_fma_f32 v[132:133], v[44:45], v[126:127], v[28:29] op_sel_hi:[1,0,1]
	v_pk_fma_f32 v[130:131], v[42:43], v[126:127], v[26:27] op_sel_hi:[1,0,1]
	v_pk_fma_f32 v[128:129], v[40:41], v[126:127], v[24:25] op_sel_hi:[1,0,1]
	s_cbranch_vccnz .LBB0_216
	s_add_i32 s0, s61, -6
	s_cmp_gt_u32 s0, 2
	s_cselect_b64 s[0:1], -1, 0
	s_xor_b64 s[36:37], s[34:35], -1
	s_and_b64 s[0:1], s[36:37], s[0:1]
	s_and_b64 vcc, exec, s[0:1]
	s_cbranch_vccnz .LBB0_216
	v_mbcnt_hi_u32_b32 v125, -1, v207
	v_and_b32_e32 v136, 64, v125
	v_xor_b32_e32 v127, 16, v125
	v_add_u32_e32 v136, 64, v136
	v_cmp_lt_i32_e32 vcc, v127, v136
	s_nop 1
	v_cndmask_b32_e32 v125, v125, v127, vcc
	v_lshlrev_b32_e32 v125, 2, v125
	ds_bpermute_b32 v140, v125, v132
	ds_bpermute_b32 v136, v125, v128
	ds_bpermute_b32 v141, v125, v133
	ds_bpermute_b32 v137, v125, v129
	ds_bpermute_b32 v142, v125, v134
	ds_bpermute_b32 v138, v125, v130
	ds_bpermute_b32 v143, v125, v135
	ds_bpermute_b32 v139, v125, v131
	s_and_saveexec_b64 s[0:1], s[40:41]
	s_cbranch_execz .LBB0_215
	v_lshl_add_u64 v[160:161], s[14:15], 0, v[120:121]
	global_load_dwordx4 v[144:147], v[160:161], off offset:32
	global_load_dwordx4 v[148:151], v[160:161], off offset:48
	global_load_dwordx4 v[190:193], v[160:161], off
	global_load_dwordx4 v[194:197], v[160:161], off offset:16
	s_waitcnt vmcnt(3) lgkmcnt(1)
	v_pk_mul_f32 v[142:143], v[146:147], v[142:143]
	v_pk_mul_f32 v[140:141], v[144:145], v[140:141]
	s_waitcnt vmcnt(2) lgkmcnt(0)
	v_pk_mul_f32 v[138:139], v[150:151], v[138:139]
	v_pk_mul_f32 v[136:137], v[148:149], v[136:137]
	v_pk_mul_f32 v[140:141], v[174:175], v[140:141]
	v_pk_mul_f32 v[142:143], v[176:177], v[142:143]
	v_pk_mul_f32 v[136:137], v[174:175], v[136:137]
	v_pk_mul_f32 v[138:139], v[176:177], v[138:139]
	s_waitcnt vmcnt(1)
	v_pk_fma_f32 v[134:135], v[134:135], v[192:193], v[142:143]
	v_pk_fma_f32 v[132:133], v[132:133], v[190:191], v[140:141]
	s_waitcnt vmcnt(0)
	v_pk_fma_f32 v[130:131], v[130:131], v[196:197], v[138:139]
	v_pk_fma_f32 v[128:129], v[128:129], v[194:195], v[136:137]

.LBB0_216:
	v_pk_mul_f32 v[134:135], v[122:123], v[134:135]
	v_pk_mul_f32 v[122:123], v[122:123], v[130:131]
	v_pk_mul_f32 v[130:131], v[186:187], v[128:129]
	v_mov_b32_e32 v127, v126
	v_mad_i64_i32 v[124:125], s[0:1], s30, v124, 0
	v_pk_mul_f32 v[132:133], v[186:187], v[132:133]
	v_cvt_pk_bf16_f32 v130, v130, v131
	v_cvt_pk_bf16_f32 v131, v122, v123
	v_mov_b32_e32 v122, v126
	v_mov_b32_e32 v123, v126
	v_lshl_add_u64 v[124:125], v[124:125], 1, v[188:189]
	v_cvt_pk_bf16_f32 v128, v132, v133
	v_cvt_pk_bf16_f32 v129, v134, v135
	v_pk_fma_f32 v[118:119], v[118:119], v[122:123], v[110:111]
	v_pk_fma_f32 v[116:117], v[116:117], v[126:127], v[108:109]
	v_pk_fma_f32 v[122:123], v[114:115], v[122:123], v[106:107]
	s_and_b64 vcc, exec, s[46:47]
	v_pk_fma_f32 v[112:113], v[112:113], v[126:127], v[104:105]
	global_store_dwordx4 v[124:125], v[128:131], off nt
	s_cbranch_vccnz .LBB0_220
	v_mbcnt_hi_u32_b32 v114, -1, v207
	v_and_b32_e32 v126, 64, v114
	v_xor_b32_e32 v115, 16, v114
	v_add_u32_e32 v126, 64, v126
	v_cmp_lt_i32_e32 vcc, v115, v126
	s_nop 1
	v_cndmask_b32_e32 v114, v114, v115, vcc
	v_lshlrev_b32_e32 v127, 2, v114
	ds_bpermute_b32 v128, v127, v116
	ds_bpermute_b32 v114, v127, v112
	ds_bpermute_b32 v129, v127, v117
	ds_bpermute_b32 v115, v127, v113
	ds_bpermute_b32 v130, v127, v118
	ds_bpermute_b32 v126, v127, v122
	ds_bpermute_b32 v131, v127, v119
	ds_bpermute_b32 v127, v127, v123
	s_and_saveexec_b64 s[0:1], s[40:41]
	s_cbranch_execz .LBB0_219
	v_lshl_add_u64 v[120:121], s[14:15], 0, v[120:121]
	global_load_dwordx4 v[132:135], v[120:121], off offset:32
	s_waitcnt lgkmcnt(8)
	global_load_dwordx4 v[136:139], v[120:121], off offset:48
	global_load_dwordx4 v[140:143], v[120:121], off
	global_load_dwordx4 v[144:147], v[120:121], off offset:16
	s_waitcnt vmcnt(3) lgkmcnt(1)
	v_pk_mul_f32 v[120:121], v[134:135], v[130:131]
	v_pk_mul_f32 v[128:129], v[132:133], v[128:129]
	s_waitcnt vmcnt(2) lgkmcnt(0)
	v_pk_mul_f32 v[126:127], v[138:139], v[126:127]
	v_pk_mul_f32 v[114:115], v[136:137], v[114:115]
	v_pk_mul_f32 v[128:129], v[174:175], v[128:129]
	v_pk_mul_f32 v[120:121], v[176:177], v[120:121]
	v_pk_mul_f32 v[114:115], v[174:175], v[114:115]
	v_pk_mul_f32 v[126:127], v[176:177], v[126:127]
	s_waitcnt vmcnt(1)
	v_pk_fma_f32 v[118:119], v[118:119], v[142:143], v[120:121]
	v_pk_fma_f32 v[116:117], v[116:117], v[140:141], v[128:129]
	s_waitcnt vmcnt(0)
	v_pk_fma_f32 v[122:123], v[122:123], v[146:147], v[126:127]
	v_pk_fma_f32 v[112:113], v[112:113], v[144:145], v[114:115]

.LBB0_220:
	s_waitcnt lgkmcnt(6)
	v_mov_b32_e32 v114, v186
	s_waitcnt lgkmcnt(4)
	v_mov_b32_e32 v115, v186
	v_pk_mul_f32 v[118:119], v[114:115], v[118:119]
	v_pk_mul_f32 v[116:117], v[186:187], v[116:117]
	v_pk_mul_f32 v[120:121], v[114:115], v[122:123]
	v_pk_mul_f32 v[112:113], v[186:187], v[112:113]
	v_cvt_pk_bf16_f32 v116, v116, v117
	v_cvt_pk_bf16_f32 v117, v118, v119
	v_cvt_pk_bf16_f32 v118, v112, v113
	v_cvt_pk_bf16_f32 v119, v120, v121
	global_store_dwordx4 v[124:125], v[116:119], off offset:256 nt
	s_and_b64 vcc, exec, s[44:45]
	s_nop 0
	v_add_u32_e32 v116, 0x90, v184
	v_ashrrev_i32_e32 v117, 31, v116
	v_lshlrev_b64 v[112:113], 6, v[116:117]
	s_waitcnt lgkmcnt(1)
	v_lshl_add_u64 v[130:131], s[12:13], 0, v[112:113]
	global_load_dwordx4 v[118:121], v[130:131], off
	global_load_dwordx4 v[122:125], v[130:131], off offset:32
	s_waitcnt lgkmcnt(0)
	global_load_dwordx4 v[126:129], v[130:131], off offset:16
	s_nop 0
	global_load_dwordx4 v[130:133], v[130:131], off offset:48
	s_waitcnt vmcnt(3)
	v_mov_b32_e32 v134, v118
	s_waitcnt vmcnt(2)
	v_mov_b32_e32 v135, v122
	v_mov_b32_e32 v122, v119
	v_mov_b32_e32 v118, v120
	v_mov_b32_e32 v119, v124
	v_mov_b32_e32 v124, v121
	s_waitcnt vmcnt(1)
	v_mov_b32_e32 v120, v126
	s_waitcnt vmcnt(0)
	v_mov_b32_e32 v121, v130
	v_mov_b32_e32 v130, v127
	v_mov_b32_e32 v126, v128
	v_mov_b32_e32 v127, v132
	v_mov_b32_e32 v132, v129
	v_pk_add_f32 v[122:123], v[134:135], v[122:123]
	v_pk_add_f32 v[118:119], v[118:119], v[124:125]
	v_pk_add_f32 v[120:121], v[120:121], v[130:131]
	v_pk_add_f32 v[124:125], v[126:127], v[132:133]
	v_pk_add_f32 v[118:119], v[122:123], v[118:119]
	v_pk_add_f32 v[120:121], v[120:121], v[124:125]
	s_nop 0
	v_pk_add_f32 v[118:119], v[118:119], v[120:121]
	s_nop 0
	v_add_f32_e32 v117, v118, v119
	v_fmamk_f32 v117, v117, 0x3a800000, v208
	v_mul_f32_e32 v118, 0x4b800000, v117
	v_cmp_gt_f32_e64 s[0:1], s94, v117
	s_nop 1
	v_cndmask_b32_e64 v117, v117, v118, s[0:1]
	v_rsq_f32_e32 v117, v117
	s_nop 0
	v_mul_f32_e32 v118, 0x45800000, v117
	v_cndmask_b32_e64 v118, v117, v118, s[0:1]
	v_pk_fma_f32 v[126:127], v[38:39], v[118:119], v[30:31] op_sel_hi:[1,0,1]
	v_pk_fma_f32 v[124:125], v[36:37], v[118:119], v[28:29] op_sel_hi:[1,0,1]
	v_pk_fma_f32 v[122:123], v[34:35], v[118:119], v[26:27] op_sel_hi:[1,0,1]
	v_pk_fma_f32 v[120:121], v[32:33], v[118:119], v[24:25] op_sel_hi:[1,0,1]
	s_cbranch_vccnz .LBB0_225
	s_add_i32 s0, s61, -6
	s_cmp_gt_u32 s0, 2
	s_cselect_b64 s[0:1], -1, 0
	s_xor_b64 s[36:37], s[34:35], -1
	s_and_b64 s[0:1], s[36:37], s[0:1]
	s_and_b64 vcc, exec, s[0:1]
	s_cbranch_vccnz .LBB0_225
	v_mbcnt_hi_u32_b32 v117, -1, v207
	v_and_b32_e32 v128, 64, v117
	v_xor_b32_e32 v119, 16, v117
	v_add_u32_e32 v128, 64, v128
	v_cmp_lt_i32_e32 vcc, v119, v128
	s_nop 1
	v_cndmask_b32_e32 v117, v117, v119, vcc
	v_lshlrev_b32_e32 v117, 2, v117
	ds_bpermute_b32 v132, v117, v124
	ds_bpermute_b32 v128, v117, v120
	ds_bpermute_b32 v133, v117, v125
	ds_bpermute_b32 v129, v117, v121
	ds_bpermute_b32 v134, v117, v126
	ds_bpermute_b32 v130, v117, v122
	ds_bpermute_b32 v135, v117, v127
	ds_bpermute_b32 v131, v117, v123
	s_and_saveexec_b64 s[0:1], s[40:41]
	s_cbranch_execz .LBB0_224
	v_lshl_add_u64 v[148:149], s[14:15], 0, v[112:113]
	global_load_dwordx4 v[136:139], v[148:149], off offset:32
	global_load_dwordx4 v[140:143], v[148:149], off offset:48
	global_load_dwordx4 v[144:147], v[148:149], off
	s_nop 0
	global_load_dwordx4 v[148:151], v[148:149], off offset:16
	s_waitcnt vmcnt(3) lgkmcnt(1)
	v_pk_mul_f32 v[134:135], v[138:139], v[134:135]
	v_pk_mul_f32 v[132:133], v[136:137], v[132:133]
	s_waitcnt vmcnt(2) lgkmcnt(0)
	v_pk_mul_f32 v[130:131], v[142:143], v[130:131]
	v_pk_mul_f32 v[128:129], v[140:141], v[128:129]
	v_pk_mul_f32 v[132:133], v[174:175], v[132:133]
	v_pk_mul_f32 v[134:135], v[176:177], v[134:135]
	v_pk_mul_f32 v[128:129], v[174:175], v[128:129]
	v_pk_mul_f32 v[130:131], v[176:177], v[130:131]
	s_waitcnt vmcnt(1)
	v_pk_fma_f32 v[126:127], v[126:127], v[146:147], v[134:135]
	v_pk_fma_f32 v[124:125], v[124:125], v[144:145], v[132:133]
	s_waitcnt vmcnt(0)
	v_pk_fma_f32 v[122:123], v[122:123], v[150:151], v[130:131]
	v_pk_fma_f32 v[120:121], v[120:121], v[148:149], v[128:129]

.LBB0_225:
	v_pk_mul_f32 v[126:127], v[114:115], v[126:127]
	v_pk_mul_f32 v[114:115], v[114:115], v[122:123]
	v_pk_mul_f32 v[122:123], v[186:187], v[120:121]
	v_mov_b32_e32 v119, v118
	v_mad_i64_i32 v[116:117], s[0:1], s30, v116, 0
	v_pk_mul_f32 v[124:125], v[186:187], v[124:125]
	v_cvt_pk_bf16_f32 v122, v122, v123
	v_cvt_pk_bf16_f32 v123, v114, v115
	v_mov_b32_e32 v114, v118
	v_mov_b32_e32 v115, v118
	v_lshl_add_u64 v[116:117], v[116:117], 1, v[188:189]
	v_cvt_pk_bf16_f32 v120, v124, v125
	v_cvt_pk_bf16_f32 v121, v126, v127
	v_pk_fma_f32 v[102:103], v[102:103], v[114:115], v[110:111]
	v_pk_fma_f32 v[100:101], v[100:101], v[118:119], v[108:109]
	v_pk_fma_f32 v[114:115], v[98:99], v[114:115], v[106:107]
	s_and_b64 vcc, exec, s[46:47]
	v_pk_fma_f32 v[96:97], v[96:97], v[118:119], v[104:105]
	global_store_dwordx4 v[116:117], v[120:123], off nt
	s_cbranch_vccnz .LBB0_229
	v_mbcnt_hi_u32_b32 v98, -1, v207
	v_and_b32_e32 v118, 64, v98
	v_xor_b32_e32 v99, 16, v98
	v_add_u32_e32 v118, 64, v118
	v_cmp_lt_i32_e32 vcc, v99, v118
	s_nop 1
	v_cndmask_b32_e32 v98, v98, v99, vcc
	v_lshlrev_b32_e32 v119, 2, v98
	ds_bpermute_b32 v120, v119, v100
	ds_bpermute_b32 v98, v119, v96
	ds_bpermute_b32 v121, v119, v101
	ds_bpermute_b32 v99, v119, v97
	ds_bpermute_b32 v122, v119, v102
	ds_bpermute_b32 v118, v119, v114
	ds_bpermute_b32 v123, v119, v103
	ds_bpermute_b32 v119, v119, v115
	s_and_saveexec_b64 s[0:1], s[40:41]
	s_cbranch_execz .LBB0_228
	v_lshl_add_u64 v[112:113], s[14:15], 0, v[112:113]
	global_load_dwordx4 v[124:127], v[112:113], off offset:32
	s_waitcnt lgkmcnt(8)
	global_load_dwordx4 v[128:131], v[112:113], off offset:48
	global_load_dwordx4 v[132:135], v[112:113], off
	global_load_dwordx4 v[136:139], v[112:113], off offset:16
	s_waitcnt vmcnt(3) lgkmcnt(1)
	v_pk_mul_f32 v[112:113], v[126:127], v[122:123]
	v_pk_mul_f32 v[120:121], v[124:125], v[120:121]
	s_waitcnt vmcnt(2) lgkmcnt(0)
	v_pk_mul_f32 v[118:119], v[130:131], v[118:119]
	v_pk_mul_f32 v[98:99], v[128:129], v[98:99]
	v_pk_mul_f32 v[120:121], v[174:175], v[120:121]
	v_pk_mul_f32 v[112:113], v[176:177], v[112:113]
	v_pk_mul_f32 v[98:99], v[174:175], v[98:99]
	v_pk_mul_f32 v[118:119], v[176:177], v[118:119]
	s_waitcnt vmcnt(1)
	v_pk_fma_f32 v[102:103], v[102:103], v[134:135], v[112:113]
	v_pk_fma_f32 v[100:101], v[100:101], v[132:133], v[120:121]
	s_waitcnt vmcnt(0)
	v_pk_fma_f32 v[114:115], v[114:115], v[138:139], v[118:119]
	v_pk_fma_f32 v[96:97], v[96:97], v[136:137], v[98:99]

.LBB0_229:
	s_waitcnt lgkmcnt(6)
	v_mov_b32_e32 v98, v186
	s_waitcnt lgkmcnt(4)
	v_mov_b32_e32 v99, v186
	v_pk_mul_f32 v[102:103], v[98:99], v[102:103]
	v_pk_mul_f32 v[100:101], v[186:187], v[100:101]
	v_pk_mul_f32 v[112:113], v[98:99], v[114:115]
	v_pk_mul_f32 v[96:97], v[186:187], v[96:97]
	v_cvt_pk_bf16_f32 v100, v100, v101
	v_cvt_pk_bf16_f32 v101, v102, v103
	v_cvt_pk_bf16_f32 v102, v96, v97
	v_cvt_pk_bf16_f32 v103, v112, v113
	global_store_dwordx4 v[116:117], v[100:103], off offset:256 nt
	s_and_b64 vcc, exec, s[44:45]
	s_nop 0
	v_add_u32_e32 v100, 0xa0, v184
	v_ashrrev_i32_e32 v101, 31, v100
	v_lshlrev_b64 v[96:97], 6, v[100:101]
	v_lshl_add_u64 v[102:103], s[12:13], 0, v[96:97]
	global_load_dwordx4 v[112:115], v[102:103], off
	s_waitcnt lgkmcnt(0)
	global_load_dwordx4 v[116:119], v[102:103], off offset:32
	global_load_dwordx4 v[120:123], v[102:103], off offset:16
	global_load_dwordx4 v[124:127], v[102:103], off offset:48
	s_waitcnt vmcnt(3)
	v_mov_b32_e32 v102, v112
	s_waitcnt vmcnt(2)
	v_mov_b32_e32 v103, v116
	v_mov_b32_e32 v116, v113
	v_mov_b32_e32 v112, v114
	v_mov_b32_e32 v113, v118
	v_mov_b32_e32 v118, v115
	s_waitcnt vmcnt(1)
	v_mov_b32_e32 v114, v120
	s_waitcnt vmcnt(0)
	v_mov_b32_e32 v115, v124
	v_mov_b32_e32 v124, v121
	v_mov_b32_e32 v120, v122
	v_mov_b32_e32 v121, v126
	v_mov_b32_e32 v126, v123
	v_pk_add_f32 v[102:103], v[102:103], v[116:117]
	v_pk_add_f32 v[112:113], v[112:113], v[118:119]
	v_pk_add_f32 v[114:115], v[114:115], v[124:125]
	v_pk_add_f32 v[116:117], v[120:121], v[126:127]
	v_pk_add_f32 v[102:103], v[102:103], v[112:113]
	v_pk_add_f32 v[112:113], v[114:115], v[116:117]
	s_nop 0
	v_pk_add_f32 v[102:103], v[102:103], v[112:113]
	s_nop 0
	v_add_f32_e32 v101, v102, v103
	v_fmamk_f32 v101, v101, 0x3a800000, v208
	v_mul_f32_e32 v102, 0x4b800000, v101
	v_cmp_gt_f32_e64 s[0:1], s94, v101
	s_nop 1
	v_cndmask_b32_e64 v101, v101, v102, s[0:1]
	v_rsq_f32_e32 v101, v101
	s_nop 0
	v_mul_f32_e32 v102, 0x45800000, v101
	v_cndmask_b32_e64 v102, v101, v102, s[0:1]
	v_pk_fma_f32 v[118:119], v[22:23], v[102:103], v[30:31] op_sel_hi:[1,0,1]
	v_pk_fma_f32 v[116:117], v[20:21], v[102:103], v[28:29] op_sel_hi:[1,0,1]
	v_pk_fma_f32 v[114:115], v[18:19], v[102:103], v[26:27] op_sel_hi:[1,0,1]
	v_pk_fma_f32 v[112:113], v[16:17], v[102:103], v[24:25] op_sel_hi:[1,0,1]
	s_cbranch_vccnz .LBB0_234
	s_add_i32 s0, s61, -6
	s_cmp_gt_u32 s0, 2
	s_cselect_b64 s[0:1], -1, 0
	s_xor_b64 s[36:37], s[34:35], -1
	s_and_b64 s[0:1], s[36:37], s[0:1]
	s_and_b64 vcc, exec, s[0:1]
	s_cbranch_vccnz .LBB0_234
	v_mbcnt_hi_u32_b32 v101, -1, v207
	v_and_b32_e32 v120, 64, v101
	v_xor_b32_e32 v103, 16, v101
	v_add_u32_e32 v120, 64, v120
	v_cmp_lt_i32_e32 vcc, v103, v120
	s_nop 1
	v_cndmask_b32_e32 v101, v101, v103, vcc
	v_lshlrev_b32_e32 v101, 2, v101
	ds_bpermute_b32 v124, v101, v116
	ds_bpermute_b32 v120, v101, v112
	ds_bpermute_b32 v125, v101, v117
	ds_bpermute_b32 v121, v101, v113
	ds_bpermute_b32 v126, v101, v118
	ds_bpermute_b32 v122, v101, v114
	ds_bpermute_b32 v127, v101, v119
	ds_bpermute_b32 v123, v101, v115
	s_and_saveexec_b64 s[0:1], s[40:41]
	s_cbranch_execz .LBB0_233
	v_lshl_add_u64 v[140:141], s[14:15], 0, v[96:97]
	global_load_dwordx4 v[128:131], v[140:141], off offset:32
	global_load_dwordx4 v[132:135], v[140:141], off offset:48
	global_load_dwordx4 v[136:139], v[140:141], off
	s_nop 0
	global_load_dwordx4 v[140:143], v[140:141], off offset:16
	s_waitcnt vmcnt(3) lgkmcnt(1)
	v_pk_mul_f32 v[126:127], v[130:131], v[126:127]
	v_pk_mul_f32 v[124:125], v[128:129], v[124:125]
	s_waitcnt vmcnt(2) lgkmcnt(0)
	v_pk_mul_f32 v[122:123], v[134:135], v[122:123]
	v_pk_mul_f32 v[120:121], v[132:133], v[120:121]
	v_pk_mul_f32 v[124:125], v[174:175], v[124:125]
	v_pk_mul_f32 v[126:127], v[176:177], v[126:127]
	v_pk_mul_f32 v[120:121], v[174:175], v[120:121]
	v_pk_mul_f32 v[122:123], v[176:177], v[122:123]
	s_waitcnt vmcnt(1)
	v_pk_fma_f32 v[118:119], v[118:119], v[138:139], v[126:127]
	v_pk_fma_f32 v[116:117], v[116:117], v[136:137], v[124:125]
	s_waitcnt vmcnt(0)
	v_pk_fma_f32 v[114:115], v[114:115], v[142:143], v[122:123]
	v_pk_fma_f32 v[112:113], v[112:113], v[140:141], v[120:121]

.LBB0_234:
	v_pk_mul_f32 v[118:119], v[98:99], v[118:119]
	v_pk_mul_f32 v[98:99], v[98:99], v[114:115]
	v_pk_mul_f32 v[114:115], v[186:187], v[112:113]
	v_mov_b32_e32 v103, v102
	v_mad_i64_i32 v[100:101], s[0:1], s30, v100, 0
	v_pk_mul_f32 v[116:117], v[186:187], v[116:117]
	v_cvt_pk_bf16_f32 v114, v114, v115
	v_cvt_pk_bf16_f32 v115, v98, v99
	v_mov_b32_e32 v98, v102
	v_mov_b32_e32 v99, v102
	v_lshl_add_u64 v[100:101], v[100:101], 1, v[188:189]
	v_cvt_pk_bf16_f32 v112, v116, v117
	v_cvt_pk_bf16_f32 v113, v118, v119
	v_pk_fma_f32 v[94:95], v[94:95], v[98:99], v[110:111]
	v_pk_fma_f32 v[92:93], v[92:93], v[102:103], v[108:109]
	v_pk_fma_f32 v[98:99], v[90:91], v[98:99], v[106:107]
	s_and_b64 vcc, exec, s[46:47]
	v_pk_fma_f32 v[88:89], v[88:89], v[102:103], v[104:105]
	global_store_dwordx4 v[100:101], v[112:115], off nt
	s_cbranch_vccnz .LBB0_238
	v_mbcnt_hi_u32_b32 v90, -1, v207
	v_and_b32_e32 v102, 64, v90
	v_xor_b32_e32 v91, 16, v90
	v_add_u32_e32 v102, 64, v102
	v_cmp_lt_i32_e32 vcc, v91, v102
	s_nop 1
	v_cndmask_b32_e32 v90, v90, v91, vcc
	v_lshlrev_b32_e32 v103, 2, v90
	ds_bpermute_b32 v112, v103, v92
	ds_bpermute_b32 v90, v103, v88
	ds_bpermute_b32 v113, v103, v93
	ds_bpermute_b32 v91, v103, v89
	ds_bpermute_b32 v114, v103, v94
	ds_bpermute_b32 v102, v103, v98
	ds_bpermute_b32 v115, v103, v95
	ds_bpermute_b32 v103, v103, v99
	s_and_saveexec_b64 s[0:1], s[40:41]
	s_cbranch_execz .LBB0_237
	v_lshl_add_u64 v[96:97], s[14:15], 0, v[96:97]
	global_load_dwordx4 v[116:119], v[96:97], off offset:32
	s_waitcnt lgkmcnt(8)
	global_load_dwordx4 v[120:123], v[96:97], off offset:48
	global_load_dwordx4 v[124:127], v[96:97], off
	global_load_dwordx4 v[128:131], v[96:97], off offset:16
	s_waitcnt vmcnt(3) lgkmcnt(1)
	v_pk_mul_f32 v[96:97], v[118:119], v[114:115]
	v_pk_mul_f32 v[112:113], v[116:117], v[112:113]
	s_waitcnt vmcnt(2) lgkmcnt(0)
	v_pk_mul_f32 v[102:103], v[122:123], v[102:103]
	v_pk_mul_f32 v[90:91], v[120:121], v[90:91]
	v_pk_mul_f32 v[112:113], v[174:175], v[112:113]
	v_pk_mul_f32 v[96:97], v[176:177], v[96:97]
	v_pk_mul_f32 v[90:91], v[174:175], v[90:91]
	v_pk_mul_f32 v[102:103], v[176:177], v[102:103]
	s_waitcnt vmcnt(1)
	v_pk_fma_f32 v[94:95], v[94:95], v[126:127], v[96:97]
	v_pk_fma_f32 v[92:93], v[92:93], v[124:125], v[112:113]
	s_waitcnt vmcnt(0)
	v_pk_fma_f32 v[98:99], v[98:99], v[130:131], v[102:103]
	v_pk_fma_f32 v[88:89], v[88:89], v[128:129], v[90:91]

.LBB0_238:
	s_waitcnt lgkmcnt(6)
	v_mov_b32_e32 v90, v186
	s_waitcnt lgkmcnt(4)
	v_mov_b32_e32 v91, v186
	v_pk_mul_f32 v[94:95], v[90:91], v[94:95]
	v_pk_mul_f32 v[92:93], v[186:187], v[92:93]
	v_pk_mul_f32 v[96:97], v[90:91], v[98:99]
	v_pk_mul_f32 v[88:89], v[186:187], v[88:89]
	v_cvt_pk_bf16_f32 v92, v92, v93
	v_cvt_pk_bf16_f32 v93, v94, v95
	v_cvt_pk_bf16_f32 v94, v88, v89
	v_cvt_pk_bf16_f32 v95, v96, v97
	global_store_dwordx4 v[100:101], v[92:95], off offset:256 nt
	s_and_b64 vcc, exec, s[44:45]
	s_nop 0
	v_add_u32_e32 v92, 0xb0, v184
	v_ashrrev_i32_e32 v93, 31, v92
	v_lshlrev_b64 v[88:89], 6, v[92:93]
	s_waitcnt lgkmcnt(0)
	v_lshl_add_u64 v[102:103], s[12:13], 0, v[88:89]
	global_load_dwordx4 v[94:97], v[102:103], off
	global_load_dwordx4 v[98:101], v[102:103], off offset:32
	global_load_dwordx4 v[112:115], v[102:103], off offset:16
	global_load_dwordx4 v[116:119], v[102:103], off offset:48
	s_waitcnt vmcnt(3)
	v_mov_b32_e32 v102, v94
	s_waitcnt vmcnt(2)
	v_mov_b32_e32 v103, v98
	v_mov_b32_e32 v98, v95
	v_mov_b32_e32 v94, v96
	v_mov_b32_e32 v95, v100
	v_mov_b32_e32 v100, v97
	s_waitcnt vmcnt(1)
	v_mov_b32_e32 v96, v112
	s_waitcnt vmcnt(0)
	v_mov_b32_e32 v97, v116
	v_mov_b32_e32 v116, v113
	v_mov_b32_e32 v112, v114
	v_mov_b32_e32 v113, v118
	v_mov_b32_e32 v118, v115
	v_pk_add_f32 v[98:99], v[102:103], v[98:99]
	v_pk_add_f32 v[94:95], v[94:95], v[100:101]
	v_pk_add_f32 v[96:97], v[96:97], v[116:117]
	v_pk_add_f32 v[100:101], v[112:113], v[118:119]
	v_pk_add_f32 v[94:95], v[98:99], v[94:95]
	v_pk_add_f32 v[96:97], v[96:97], v[100:101]
	s_nop 0
	v_pk_add_f32 v[94:95], v[94:95], v[96:97]
	s_nop 0
	v_add_f32_e32 v93, v94, v95
	v_fmamk_f32 v93, v93, 0x3a800000, v208
	v_mul_f32_e32 v94, 0x4b800000, v93
	v_cmp_gt_f32_e64 s[0:1], s94, v93
	s_nop 1
	v_cndmask_b32_e64 v93, v93, v94, s[0:1]
	v_rsq_f32_e32 v93, v93
	s_nop 0
	v_mul_f32_e32 v94, 0x45800000, v93
	v_cndmask_b32_e64 v94, v93, v94, s[0:1]
	v_pk_fma_f32 v[102:103], v[14:15], v[94:95], v[30:31] op_sel_hi:[1,0,1]
	v_pk_fma_f32 v[100:101], v[12:13], v[94:95], v[28:29] op_sel_hi:[1,0,1]
	v_pk_fma_f32 v[98:99], v[10:11], v[94:95], v[26:27] op_sel_hi:[1,0,1]
	v_pk_fma_f32 v[96:97], v[8:9], v[94:95], v[24:25] op_sel_hi:[1,0,1]
	s_cbranch_vccnz .LBB0_243
	s_add_i32 s61, s61, -6
	s_cmp_gt_u32 s61, 2
	s_cselect_b64 s[0:1], -1, 0
	s_xor_b64 s[34:35], s[34:35], -1
	s_and_b64 s[0:1], s[34:35], s[0:1]
	s_and_b64 vcc, exec, s[0:1]
	s_cbranch_vccnz .LBB0_243
	v_mbcnt_hi_u32_b32 v93, -1, v207
	v_and_b32_e32 v112, 64, v93
	v_xor_b32_e32 v95, 16, v93
	v_add_u32_e32 v112, 64, v112
	v_cmp_lt_i32_e32 vcc, v95, v112
	s_nop 1
	v_cndmask_b32_e32 v93, v93, v95, vcc
	v_lshlrev_b32_e32 v93, 2, v93
	ds_bpermute_b32 v116, v93, v100
	ds_bpermute_b32 v112, v93, v96
	ds_bpermute_b32 v117, v93, v101
	ds_bpermute_b32 v113, v93, v97
	ds_bpermute_b32 v118, v93, v102
	ds_bpermute_b32 v114, v93, v98
	ds_bpermute_b32 v119, v93, v103
	ds_bpermute_b32 v115, v93, v99
	s_and_saveexec_b64 s[0:1], s[40:41]
	s_cbranch_execz .LBB0_242
	v_lshl_add_u64 v[132:133], s[14:15], 0, v[88:89]
	global_load_dwordx4 v[120:123], v[132:133], off offset:32
	global_load_dwordx4 v[124:127], v[132:133], off offset:48
	global_load_dwordx4 v[128:131], v[132:133], off
	s_nop 0
	global_load_dwordx4 v[132:135], v[132:133], off offset:16
	s_waitcnt vmcnt(3) lgkmcnt(1)
	v_pk_mul_f32 v[118:119], v[122:123], v[118:119]
	v_pk_mul_f32 v[116:117], v[120:121], v[116:117]
	s_waitcnt vmcnt(2) lgkmcnt(0)
	v_pk_mul_f32 v[114:115], v[126:127], v[114:115]
	v_pk_mul_f32 v[112:113], v[124:125], v[112:113]
	v_pk_mul_f32 v[116:117], v[174:175], v[116:117]
	v_pk_mul_f32 v[118:119], v[176:177], v[118:119]
	v_pk_mul_f32 v[112:113], v[174:175], v[112:113]
	v_pk_mul_f32 v[114:115], v[176:177], v[114:115]
	s_waitcnt vmcnt(1)
	v_pk_fma_f32 v[102:103], v[102:103], v[130:131], v[118:119]
	v_pk_fma_f32 v[100:101], v[100:101], v[128:129], v[116:117]
	s_waitcnt vmcnt(0)
	v_pk_fma_f32 v[98:99], v[98:99], v[134:135], v[114:115]
	v_pk_fma_f32 v[96:97], v[96:97], v[132:133], v[112:113]

.LBB0_243:
	v_pk_mul_f32 v[102:103], v[90:91], v[102:103]
	v_pk_mul_f32 v[90:91], v[90:91], v[98:99]
	v_pk_mul_f32 v[98:99], v[186:187], v[96:97]
	v_mov_b32_e32 v95, v94
	v_mad_i64_i32 v[92:93], s[0:1], s30, v92, 0
	v_pk_mul_f32 v[100:101], v[186:187], v[100:101]
	v_cvt_pk_bf16_f32 v98, v98, v99
	v_cvt_pk_bf16_f32 v99, v90, v91
	v_mov_b32_e32 v90, v94
	v_mov_b32_e32 v91, v94
	v_lshl_add_u64 v[92:93], v[92:93], 1, v[188:189]
	v_cvt_pk_bf16_f32 v96, v100, v101
	v_cvt_pk_bf16_f32 v97, v102, v103
	v_pk_fma_f32 v[86:87], v[86:87], v[90:91], v[110:111]
	v_pk_fma_f32 v[84:85], v[84:85], v[94:95], v[108:109]
	v_pk_fma_f32 v[82:83], v[82:83], v[90:91], v[106:107]
	s_and_b64 vcc, exec, s[46:47]
	v_pk_fma_f32 v[80:81], v[80:81], v[94:95], v[104:105]
	global_store_dwordx4 v[92:93], v[96:99], off nt
	s_cbranch_vccnz .LBB0_247
	v_mbcnt_hi_u32_b32 v90, -1, v207
	v_and_b32_e32 v94, 64, v90
	v_xor_b32_e32 v91, 16, v90
	v_add_u32_e32 v94, 64, v94
	v_cmp_lt_i32_e32 vcc, v91, v94
	s_nop 1
	v_cndmask_b32_e32 v90, v90, v91, vcc
	v_lshlrev_b32_e32 v95, 2, v90
	ds_bpermute_b32 v96, v95, v84
	ds_bpermute_b32 v90, v95, v80
	ds_bpermute_b32 v97, v95, v85
	ds_bpermute_b32 v91, v95, v81
	ds_bpermute_b32 v98, v95, v86
	ds_bpermute_b32 v94, v95, v82
	ds_bpermute_b32 v99, v95, v87
	ds_bpermute_b32 v95, v95, v83
	s_and_saveexec_b64 s[0:1], s[40:41]
	s_mov_b64 s[46:47], 0x8000
	s_cbranch_execz .LBB0_246
	v_lshl_add_u64 v[88:89], s[14:15], 0, v[88:89]
	global_load_dwordx4 v[100:103], v[88:89], off offset:32
	global_load_dwordx4 v[104:107], v[88:89], off offset:48
	global_load_dwordx4 v[108:111], v[88:89], off
	s_waitcnt lgkmcnt(8)
	global_load_dwordx4 v[112:115], v[88:89], off offset:16
	s_waitcnt vmcnt(3) lgkmcnt(1)
	v_pk_mul_f32 v[88:89], v[102:103], v[98:99]
	v_pk_mul_f32 v[96:97], v[100:101], v[96:97]
	s_waitcnt vmcnt(2) lgkmcnt(0)
	v_pk_mul_f32 v[94:95], v[106:107], v[94:95]
	v_pk_mul_f32 v[90:91], v[104:105], v[90:91]
	v_pk_mul_f32 v[96:97], v[174:175], v[96:97]
	v_pk_mul_f32 v[88:89], v[176:177], v[88:89]
	v_pk_mul_f32 v[90:91], v[174:175], v[90:91]
	v_pk_mul_f32 v[94:95], v[176:177], v[94:95]
	s_waitcnt vmcnt(1)
	v_pk_fma_f32 v[86:87], v[86:87], v[110:111], v[88:89]
	v_pk_fma_f32 v[84:85], v[84:85], v[108:109], v[96:97]
	s_waitcnt vmcnt(0)
	v_pk_fma_f32 v[82:83], v[82:83], v[114:115], v[94:95]
	v_pk_fma_f32 v[80:81], v[80:81], v[112:113], v[90:91]

.LBB0_248:
	v_mov_b32_e32 v88, v186
	v_mov_b32_e32 v89, v186
	v_pk_mul_f32 v[86:87], v[88:89], v[86:87]
	v_pk_mul_f32 v[84:85], v[186:187], v[84:85]
	v_pk_mul_f32 v[88:89], v[88:89], v[82:83]
	v_pk_mul_f32 v[82:83], v[186:187], v[80:81]
	v_cvt_pk_bf16_f32 v80, v84, v85
	v_cvt_pk_bf16_f32 v81, v86, v87
	v_cvt_pk_bf16_f32 v82, v82, v83
	v_cvt_pk_bf16_f32 v83, v88, v89
	global_store_dwordx4 v[92:93], v[80:83], off offset:256 nt
	s_branch .LBB0_167
.LBB0_249:
	s_and_saveexec_b64 s[30:31], s[20:21]
	s_cbranch_execz .LBB0_251
	v_ashrrev_i32_e32 v185, 31, v184
	v_lshlrev_b64 v[82:83], 6, v[184:185]
	v_lshl_add_u64 v[80:81], s[12:13], 0, v[82:83]
	global_load_dwordx4 v[84:87], v[80:81], off offset:16
	s_waitcnt lgkmcnt(0)
	global_load_dwordx4 v[88:91], v[80:81], off offset:48
	global_load_dwordx4 v[92:95], v[80:81], off
	global_load_dwordx4 v[96:99], v[80:81], off offset:32
	s_mov_b64 s[0:1], 0x400
	v_lshl_add_u64 v[102:103], v[82:83], 0, s[0:1]
	s_mov_b32 s0, 0x358637bd
	s_mov_b32 s34, 0x3a800000
	s_mov_b32 s23, 0x800000
	v_lshl_add_u64 v[100:101], v[178:179], 0, v[82:83]
	s_mov_b32 s94, 0x800000
	s_waitcnt vmcnt(0)
	v_mov_b32_e32 v80, v92
	v_mov_b32_e32 v81, v96
	v_mov_b32_e32 v96, v93
	v_mov_b32_e32 v92, v94
	v_mov_b32_e32 v93, v98
	v_mov_b32_e32 v98, v95
	v_pk_add_f32 v[80:81], v[80:81], v[96:97]
	v_pk_add_f32 v[92:93], v[92:93], v[98:99]
	v_lshl_add_u64 v[96:97], s[12:13], 0, v[102:103]
	v_pk_add_f32 v[80:81], v[80:81], v[92:93]
	v_mov_b32_e32 v92, v84
	v_mov_b32_e32 v93, v88
	v_mov_b32_e32 v88, v85
	v_pk_add_f32 v[84:85], v[92:93], v[88:89]
	v_mov_b32_e32 v88, v86
	v_mov_b32_e32 v89, v90
	v_mov_b32_e32 v90, v87
	v_pk_add_f32 v[86:87], v[88:89], v[90:91]
	s_nop 0
	v_pk_add_f32 v[84:85], v[84:85], v[86:87]
	s_nop 0
	v_pk_add_f32 v[80:81], v[80:81], v[84:85]
	global_load_dwordx4 v[84:87], v[96:97], off offset:16
	global_load_dwordx4 v[88:91], v[96:97], off offset:48
	global_load_dwordx4 v[92:95], v[96:97], off
	s_nop 0
	global_load_dwordx4 v[96:99], v[96:97], off offset:32
	s_waitcnt vmcnt(1)
	v_mov_b32_e32 v104, v92
	s_waitcnt vmcnt(0)
	v_mov_b32_e32 v105, v96
	v_mov_b32_e32 v96, v93
	v_pk_add_f32 v[92:93], v[104:105], v[96:97]
	v_mov_b32_e32 v96, v94
	v_mov_b32_e32 v97, v98
	v_mov_b32_e32 v98, v95
	v_pk_add_f32 v[94:95], v[96:97], v[98:99]
	s_nop 0
	v_pk_add_f32 v[92:93], v[92:93], v[94:95]
	v_mov_b32_e32 v94, v84
	v_mov_b32_e32 v95, v88
	v_mov_b32_e32 v88, v85
	v_pk_add_f32 v[84:85], v[94:95], v[88:89]
	v_mov_b32_e32 v88, v86
	v_mov_b32_e32 v89, v90
	v_mov_b32_e32 v90, v87
	v_pk_add_f32 v[86:87], v[88:89], v[90:91]
	s_nop 0
	v_pk_add_f32 v[84:85], v[84:85], v[86:87]
	v_mov_b32_e32 v87, v80
	v_pk_add_f32 v[84:85], v[92:93], v[84:85]
	s_nop 0
	v_mov_b32_e32 v86, v84
	v_mov_b32_e32 v80, v85
	v_pk_add_f32 v[84:85], v[86:87], v[80:81]
	v_mov_b64_e32 v[80:81], s[0:1]
	v_pk_fma_f32 v[84:85], v[84:85], s[34:35], v[80:81] op_sel_hi:[1,0,0]
	s_nop 0
	v_mul_f32_e32 v86, 0x4b800000, v85
	v_cmp_gt_f32_e64 s[0:1], s23, v85
	v_cmp_gt_f32_e32 vcc, s23, v84
	s_nop 0
	v_cndmask_b32_e64 v85, v85, v86, s[0:1]
	v_rsq_f32_e32 v85, v85
	s_nop 0
	v_mul_f32_e32 v86, 0x45800000, v85
	v_cndmask_b32_e64 v86, v85, v86, s[0:1]
	v_pk_fma_f32 v[74:75], v[74:75], v[86:87], v[26:27] op_sel_hi:[1,0,1]
	v_pk_fma_f32 v[72:73], v[72:73], v[86:87], v[24:25] op_sel_hi:[1,0,1]
	global_store_dwordx4 v[100:101], v[72:75], off offset:16 nt
	s_mov_b64 s[0:1], 0x800
	v_pk_fma_f32 v[78:79], v[78:79], v[86:87], v[30:31] op_sel_hi:[1,0,1]
	v_mul_f32_e32 v72, 0x4b800000, v84
	v_cndmask_b32_e32 v72, v84, v72, vcc
	v_rsq_f32_e32 v72, v72
	v_pk_fma_f32 v[76:77], v[76:77], v[86:87], v[28:29] op_sel_hi:[1,0,1]
	v_lshl_add_u64 v[74:75], v[178:179], 0, v[102:103]
	v_lshl_add_u64 v[84:85], v[82:83], 0, s[0:1]
	v_mul_f32_e32 v73, 0x45800000, v72
	v_cndmask_b32_e32 v72, v72, v73, vcc
	v_pk_fma_f32 v[70:71], v[70:71], v[72:73], v[30:31] op_sel_hi:[1,0,1]
	v_pk_fma_f32 v[68:69], v[68:69], v[72:73], v[28:29] op_sel_hi:[1,0,1]
	v_pk_fma_f32 v[66:67], v[66:67], v[72:73], v[26:27] op_sel_hi:[1,0,1]
	v_pk_fma_f32 v[64:65], v[64:65], v[72:73], v[24:25] op_sel_hi:[1,0,1]
	global_store_dwordx4 v[100:101], v[76:79], off nt
	global_store_dwordx4 v[74:75], v[68:71], off nt
	global_store_dwordx4 v[74:75], v[64:67], off offset:16 nt
	v_lshl_add_u64 v[76:77], s[12:13], 0, v[84:85]
	global_load_dwordx4 v[64:67], v[76:77], off offset:16
	global_load_dwordx4 v[68:71], v[76:77], off offset:48
	global_load_dwordx4 v[72:75], v[76:77], off
	s_nop 0
	global_load_dwordx4 v[76:79], v[76:77], off offset:32
	s_mov_b64 s[0:1], 0xc00
	v_lshl_add_u64 v[88:89], v[82:83], 0, s[0:1]
	v_lshl_add_u64 v[84:85], v[178:179], 0, v[84:85]
	s_waitcnt vmcnt(1)
	v_mov_b32_e32 v86, v72
	s_waitcnt vmcnt(0)
	v_mov_b32_e32 v87, v76
	v_mov_b32_e32 v76, v73
	v_pk_add_f32 v[72:73], v[86:87], v[76:77]
	v_mov_b32_e32 v76, v74
	v_mov_b32_e32 v77, v78
	v_mov_b32_e32 v78, v75
	v_pk_add_f32 v[74:75], v[76:77], v[78:79]
	v_lshl_add_u64 v[76:77], s[12:13], 0, v[88:89]
	v_pk_add_f32 v[72:73], v[72:73], v[74:75]
	v_mov_b32_e32 v74, v64
	v_mov_b32_e32 v75, v68
	v_mov_b32_e32 v68, v65
	v_pk_add_f32 v[64:65], v[74:75], v[68:69]
	v_mov_b32_e32 v68, v66
	v_mov_b32_e32 v69, v70
	v_mov_b32_e32 v70, v67
	v_pk_add_f32 v[66:67], v[68:69], v[70:71]
	s_nop 0
	v_pk_add_f32 v[64:65], v[64:65], v[66:67]
	s_nop 0
	v_pk_add_f32 v[86:87], v[72:73], v[64:65]
	global_load_dwordx4 v[64:67], v[76:77], off offset:16
	global_load_dwordx4 v[68:71], v[76:77], off offset:48
	global_load_dwordx4 v[72:75], v[76:77], off
	s_nop 0
	global_load_dwordx4 v[76:79], v[76:77], off offset:32
	s_waitcnt vmcnt(1)
	v_mov_b32_e32 v90, v72
	s_waitcnt vmcnt(0)
	v_mov_b32_e32 v91, v76
	v_mov_b32_e32 v76, v73
	v_pk_add_f32 v[72:73], v[90:91], v[76:77]
	v_mov_b32_e32 v76, v74
	v_mov_b32_e32 v77, v78
	v_mov_b32_e32 v78, v75
	v_pk_add_f32 v[74:75], v[76:77], v[78:79]
	s_nop 0
	v_pk_add_f32 v[72:73], v[72:73], v[74:75]
	v_mov_b32_e32 v74, v64
	v_mov_b32_e32 v75, v68
	v_mov_b32_e32 v68, v65
	v_pk_add_f32 v[64:65], v[74:75], v[68:69]
	v_mov_b32_e32 v68, v66
	v_mov_b32_e32 v69, v70
	v_mov_b32_e32 v70, v67
	v_pk_add_f32 v[66:67], v[68:69], v[70:71]
	s_nop 0
	v_pk_add_f32 v[64:65], v[64:65], v[66:67]
	v_mov_b32_e32 v67, v86
	v_pk_add_f32 v[64:65], v[72:73], v[64:65]
	s_nop 0
	v_mov_b32_e32 v66, v64
	v_mov_b32_e32 v86, v65
	v_pk_add_f32 v[64:65], v[66:67], v[86:87]
	s_nop 0
	v_pk_fma_f32 v[64:65], v[64:65], s[34:35], v[80:81] op_sel_hi:[1,0,0]
	s_nop 0
	v_mul_f32_e32 v66, 0x4b800000, v65
	v_cmp_gt_f32_e64 s[0:1], s23, v65
	v_cmp_gt_f32_e32 vcc, s23, v64
	s_nop 0
	v_cndmask_b32_e64 v65, v65, v66, s[0:1]
	v_rsq_f32_e32 v65, v65
	s_nop 0
	v_mul_f32_e32 v66, 0x45800000, v65
	v_cndmask_b32_e64 v66, v65, v66, s[0:1]
	v_pk_fma_f32 v[58:59], v[58:59], v[66:67], v[26:27] op_sel_hi:[1,0,1]
	v_pk_fma_f32 v[56:57], v[56:57], v[66:67], v[24:25] op_sel_hi:[1,0,1]
	global_store_dwordx4 v[84:85], v[56:59], off offset:16 nt
	s_mov_b64 s[0:1], 0x2000
	v_pk_fma_f32 v[62:63], v[62:63], v[66:67], v[30:31] op_sel_hi:[1,0,1]
	v_mul_f32_e32 v56, 0x4b800000, v64
	v_cndmask_b32_e32 v56, v64, v56, vcc
	v_rsq_f32_e32 v56, v56
	v_pk_fma_f32 v[60:61], v[60:61], v[66:67], v[28:29] op_sel_hi:[1,0,1]
	v_lshl_add_u64 v[58:59], v[178:179], 0, v[88:89]
	v_lshl_add_u64 v[64:65], v[82:83], 0, s[0:1]
	v_mul_f32_e32 v57, 0x45800000, v56
	v_cndmask_b32_e32 v56, v56, v57, vcc
	v_pk_fma_f32 v[54:55], v[54:55], v[56:57], v[30:31] op_sel_hi:[1,0,1]
	v_pk_fma_f32 v[52:53], v[52:53], v[56:57], v[28:29] op_sel_hi:[1,0,1]
	v_pk_fma_f32 v[50:51], v[50:51], v[56:57], v[26:27] op_sel_hi:[1,0,1]
	v_pk_fma_f32 v[48:49], v[48:49], v[56:57], v[24:25] op_sel_hi:[1,0,1]
	global_store_dwordx4 v[84:85], v[60:63], off nt
	global_store_dwordx4 v[58:59], v[52:55], off nt
	global_store_dwordx4 v[58:59], v[48:51], off offset:16 nt
	v_lshl_add_u64 v[60:61], s[12:13], 0, v[64:65]
	global_load_dwordx4 v[48:51], v[60:61], off offset:16
	global_load_dwordx4 v[52:55], v[60:61], off offset:48
	global_load_dwordx4 v[56:59], v[60:61], off
	s_nop 0
	global_load_dwordx4 v[60:63], v[60:61], off offset:32
	s_mov_b64 s[0:1], 0x2400
	v_lshl_add_u64 v[68:69], v[82:83], 0, s[0:1]
	s_waitcnt vmcnt(1)
	v_mov_b32_e32 v66, v56
	s_waitcnt vmcnt(0)
	v_mov_b32_e32 v67, v60
	v_mov_b32_e32 v60, v57
	v_pk_add_f32 v[56:57], v[66:67], v[60:61]
	v_mov_b32_e32 v60, v58
	v_mov_b32_e32 v61, v62
	v_mov_b32_e32 v62, v59
	v_pk_add_f32 v[58:59], v[60:61], v[62:63]
	s_nop 0
	v_pk_add_f32 v[56:57], v[56:57], v[58:59]
	v_mov_b32_e32 v58, v48
	v_mov_b32_e32 v59, v52
	v_mov_b32_e32 v52, v49
	v_pk_add_f32 v[48:49], v[58:59], v[52:53]
	v_mov_b32_e32 v52, v50
	v_mov_b32_e32 v53, v54
	v_mov_b32_e32 v54, v51
	v_pk_add_f32 v[50:51], v[52:53], v[54:55]
	s_nop 0
	v_pk_add_f32 v[48:49], v[48:49], v[50:51]
	s_nop 0
	v_pk_add_f32 v[50:51], v[56:57], v[48:49]
	v_lshl_add_u64 v[48:49], v[178:179], 0, v[64:65]
	v_lshl_add_u64 v[64:65], s[12:13], 0, v[68:69]
	global_load_dwordx4 v[52:55], v[64:65], off offset:16
	global_load_dwordx4 v[56:59], v[64:65], off offset:48
	global_load_dwordx4 v[60:63], v[64:65], off
	s_nop 0
	global_load_dwordx4 v[64:67], v[64:65], off offset:32
	s_waitcnt vmcnt(1)
	v_mov_b32_e32 v70, v60
	s_waitcnt vmcnt(0)
	v_mov_b32_e32 v71, v64
	v_mov_b32_e32 v64, v61
	v_pk_add_f32 v[60:61], v[70:71], v[64:65]
	v_mov_b32_e32 v64, v62
	v_mov_b32_e32 v65, v66
	v_mov_b32_e32 v66, v63
	v_pk_add_f32 v[62:63], v[64:65], v[66:67]
	s_nop 0
	v_pk_add_f32 v[60:61], v[60:61], v[62:63]
	v_mov_b32_e32 v62, v52
	v_mov_b32_e32 v63, v56
	v_mov_b32_e32 v56, v53
	v_pk_add_f32 v[52:53], v[62:63], v[56:57]
	v_mov_b32_e32 v56, v54
	v_mov_b32_e32 v57, v58
	v_mov_b32_e32 v58, v55
	v_pk_add_f32 v[54:55], v[56:57], v[58:59]
	s_nop 0
	v_pk_add_f32 v[52:53], v[52:53], v[54:55]
	v_mov_b32_e32 v55, v50
	v_pk_add_f32 v[52:53], v[60:61], v[52:53]
	s_nop 0
	v_mov_b32_e32 v54, v52
	v_mov_b32_e32 v50, v53
	v_pk_add_f32 v[50:51], v[54:55], v[50:51]
	s_nop 0
	v_pk_fma_f32 v[50:51], v[50:51], s[34:35], v[80:81] op_sel_hi:[1,0,0]
	s_nop 0
	v_mul_f32_e32 v52, 0x4b800000, v51
	v_cmp_gt_f32_e64 s[0:1], s23, v51
	v_cmp_gt_f32_e32 vcc, s23, v50
	s_nop 0
	v_cndmask_b32_e64 v51, v51, v52, s[0:1]
	v_rsq_f32_e32 v51, v51
	s_nop 0
	v_mul_f32_e32 v52, 0x45800000, v51
	v_cndmask_b32_e64 v52, v51, v52, s[0:1]
	v_pk_fma_f32 v[42:43], v[42:43], v[52:53], v[26:27] op_sel_hi:[1,0,1]
	v_pk_fma_f32 v[40:41], v[40:41], v[52:53], v[24:25] op_sel_hi:[1,0,1]
	global_store_dwordx4 v[48:49], v[40:43], off offset:16 nt
	v_pk_fma_f32 v[46:47], v[46:47], v[52:53], v[30:31] op_sel_hi:[1,0,1]
	v_pk_fma_f32 v[44:45], v[44:45], v[52:53], v[28:29] op_sel_hi:[1,0,1]
	v_mul_f32_e32 v40, 0x4b800000, v50
	v_cndmask_b32_e32 v40, v50, v40, vcc
	v_rsq_f32_e32 v40, v40
	s_mov_b64 s[0:1], 0x2800
	global_store_dwordx4 v[48:49], v[44:47], off nt
	v_lshl_add_u64 v[42:43], v[178:179], 0, v[68:69]
	v_mul_f32_e32 v41, 0x45800000, v40
	v_cndmask_b32_e32 v40, v40, v41, vcc
	v_pk_fma_f32 v[38:39], v[38:39], v[40:41], v[30:31] op_sel_hi:[1,0,1]
	v_pk_fma_f32 v[36:37], v[36:37], v[40:41], v[28:29] op_sel_hi:[1,0,1]
	v_pk_fma_f32 v[34:35], v[34:35], v[40:41], v[26:27] op_sel_hi:[1,0,1]
	v_pk_fma_f32 v[32:33], v[32:33], v[40:41], v[24:25] op_sel_hi:[1,0,1]
	v_lshl_add_u64 v[48:49], v[82:83], 0, s[0:1]
	global_store_dwordx4 v[42:43], v[36:39], off nt
	global_store_dwordx4 v[42:43], v[32:35], off offset:16 nt
	v_lshl_add_u64 v[44:45], s[12:13], 0, v[48:49]
	global_load_dwordx4 v[32:35], v[44:45], off offset:16
	global_load_dwordx4 v[36:39], v[44:45], off offset:48
	global_load_dwordx4 v[40:43], v[44:45], off
	s_nop 0
	global_load_dwordx4 v[44:47], v[44:45], off offset:32
	s_mov_b64 s[0:1], 0x2c00
	v_lshl_add_u64 v[52:53], v[82:83], 0, s[0:1]
	v_lshl_add_u64 v[48:49], v[178:179], 0, v[48:49]
	s_waitcnt vmcnt(1)
	v_mov_b32_e32 v50, v40
	s_waitcnt vmcnt(0)
	v_mov_b32_e32 v51, v44
	v_mov_b32_e32 v44, v41
	v_pk_add_f32 v[40:41], v[50:51], v[44:45]
	v_mov_b32_e32 v44, v42
	v_mov_b32_e32 v45, v46
	v_mov_b32_e32 v46, v43
	v_pk_add_f32 v[42:43], v[44:45], v[46:47]
	v_lshl_add_u64 v[44:45], s[12:13], 0, v[52:53]
	v_pk_add_f32 v[40:41], v[40:41], v[42:43]
	v_mov_b32_e32 v42, v32
	v_mov_b32_e32 v43, v36
	v_mov_b32_e32 v36, v33
	v_pk_add_f32 v[32:33], v[42:43], v[36:37]
	v_mov_b32_e32 v36, v34
	v_mov_b32_e32 v37, v38
	v_mov_b32_e32 v38, v35
	v_pk_add_f32 v[34:35], v[36:37], v[38:39]
	s_nop 0
	v_pk_add_f32 v[32:33], v[32:33], v[34:35]
	s_nop 0
	v_pk_add_f32 v[50:51], v[40:41], v[32:33]
	global_load_dwordx4 v[36:39], v[44:45], off offset:16
	global_load_dwordx4 v[32:35], v[44:45], off offset:48
	global_load_dwordx4 v[40:43], v[44:45], off
	s_nop 0
	global_load_dwordx4 v[44:47], v[44:45], off offset:32
	s_waitcnt vmcnt(1)
	v_mov_b32_e32 v54, v40
	s_waitcnt vmcnt(0)
	v_mov_b32_e32 v55, v44
	v_mov_b32_e32 v44, v41
	v_pk_add_f32 v[40:41], v[54:55], v[44:45]
	v_mov_b32_e32 v44, v42
	v_mov_b32_e32 v45, v46
	v_mov_b32_e32 v46, v43
	v_pk_add_f32 v[42:43], v[44:45], v[46:47]
	s_nop 0
	v_pk_add_f32 v[40:41], v[40:41], v[42:43]
	v_mov_b32_e32 v42, v36
	v_mov_b32_e32 v43, v32
	v_mov_b32_e32 v32, v37
	v_mov_b32_e32 v36, v38
	v_mov_b32_e32 v37, v34
	v_mov_b32_e32 v34, v39
	v_pk_add_f32 v[32:33], v[42:43], v[32:33]
	v_pk_add_f32 v[34:35], v[36:37], v[34:35]
	s_nop 0
	v_pk_add_f32 v[32:33], v[32:33], v[34:35]
	v_mov_b32_e32 v35, v50
	v_pk_add_f32 v[32:33], v[40:41], v[32:33]
	s_nop 0
	v_mov_b32_e32 v34, v32
	v_mov_b32_e32 v50, v33
	v_pk_add_f32 v[32:33], v[34:35], v[50:51]
	s_nop 0
	v_pk_fma_f32 v[32:33], v[32:33], s[34:35], v[80:81] op_sel_hi:[1,0,0]
	s_nop 0
	v_mul_f32_e32 v34, 0x4b800000, v33
	v_cmp_gt_f32_e64 s[0:1], s23, v33
	v_cmp_gt_f32_e32 vcc, s23, v32
	s_nop 0
	v_cndmask_b32_e64 v33, v33, v34, s[0:1]
	v_rsq_f32_e32 v33, v33
	s_nop 0
	v_mul_f32_e32 v34, 0x45800000, v33
	v_cndmask_b32_e64 v34, v33, v34, s[0:1]
	v_pk_fma_f32 v[18:19], v[18:19], v[34:35], v[26:27] op_sel_hi:[1,0,1]
	v_pk_fma_f32 v[16:17], v[16:17], v[34:35], v[24:25] op_sel_hi:[1,0,1]
	global_store_dwordx4 v[48:49], v[16:19], off offset:16 nt
	v_pk_fma_f32 v[22:23], v[22:23], v[34:35], v[30:31] op_sel_hi:[1,0,1]
	v_pk_fma_f32 v[20:21], v[20:21], v[34:35], v[28:29] op_sel_hi:[1,0,1]
	v_mul_f32_e32 v16, 0x4b800000, v32
	v_cndmask_b32_e32 v16, v32, v16, vcc
	v_rsq_f32_e32 v16, v16
	v_lshl_add_u64 v[18:19], v[178:179], 0, v[52:53]
	global_store_dwordx4 v[48:49], v[20:23], off nt
	v_mul_f32_e32 v17, 0x45800000, v16
	v_cndmask_b32_e32 v16, v16, v17, vcc
	v_pk_fma_f32 v[14:15], v[14:15], v[16:17], v[30:31] op_sel_hi:[1,0,1]
	v_pk_fma_f32 v[12:13], v[12:13], v[16:17], v[28:29] op_sel_hi:[1,0,1]
	v_pk_fma_f32 v[10:11], v[10:11], v[16:17], v[26:27] op_sel_hi:[1,0,1]
	v_pk_fma_f32 v[8:9], v[8:9], v[16:17], v[24:25] op_sel_hi:[1,0,1]
	global_store_dwordx4 v[18:19], v[12:15], off nt
	global_store_dwordx4 v[18:19], v[8:11], off offset:16 nt
